# fix-up phases: all slab/Hb loads of a sample row issued in one batch (1-2 round trips instead of 4)
# speedup vs baseline: 1.0149x; 1.0085x over previous
.LBB0_487:
	v_lshl_add_u64 v[4:5], s[82:83], 0, v[2:3]
	v_add_co_u32_e32 v4, vcc, 0xba67000, v4
	v_lshl_add_u64 v[8:9], s[82:83], 0, v[0:1]
	s_nop 0
	v_addc_co_u32_e32 v5, vcc, 0, v5, vcc
	v_add_co_u32_e32 v8, vcc, 0x34a77000, v8
	s_waitcnt lgkmcnt(0)
	s_nop 0
	v_addc_co_u32_e32 v9, vcc, 0, v9, vcc
	global_load_dwordx2 v[100:101], v[4:5], off offset:768
	global_load_dwordx2 v[102:103], v[4:5], off offset:1280
	global_load_dwordx2 v[104:105], v[4:5], off offset:1792
	global_load_dwordx2 v[106:107], v[4:5], off offset:2304
	v_mov_b32_e32 v10, v8
	v_mov_b32_e32 v11, v9
	global_load_dwordx4 v[108:111], v[10:11], off offset:768
	global_load_dwordx4 v[112:115], v[10:11], off offset:1792
	global_load_dwordx4 v[116:119], v[10:11], off offset:2816
	global_load_dwordx4 v[120:123], v[10:11], off offset:3840
	v_add_co_u32_e32 v10, vcc, 0x80000, v10
	s_nop 1
	v_addc_co_u32_e32 v11, vcc, 0, v11, vcc
	global_load_dwordx4 v[124:127], v[10:11], off offset:768
	global_load_dwordx4 v[128:131], v[10:11], off offset:1792
	global_load_dwordx4 v[132:135], v[10:11], off offset:2816
	global_load_dwordx4 v[136:139], v[10:11], off offset:3840
	v_add_co_u32_e32 v10, vcc, 0x80000, v10
	s_nop 1
	v_addc_co_u32_e32 v11, vcc, 0, v11, vcc
	global_load_dwordx4 v[140:143], v[10:11], off offset:768
	global_load_dwordx4 v[144:147], v[10:11], off offset:1792
	global_load_dwordx4 v[148:151], v[10:11], off offset:2816
	global_load_dwordx4 v[152:155], v[10:11], off offset:3840
	v_add_co_u32_e32 v10, vcc, 0x80000, v10
	s_nop 1
	v_addc_co_u32_e32 v11, vcc, 0, v11, vcc
	global_load_dwordx4 v[156:159], v[10:11], off offset:768
	global_load_dwordx4 v[160:163], v[10:11], off offset:1792
	global_load_dwordx4 v[164:167], v[10:11], off offset:2816
	global_load_dwordx4 v[168:171], v[10:11], off offset:3840
	v_add_co_u32_e32 v10, vcc, 0x80000, v10
	s_nop 1
	v_addc_co_u32_e32 v11, vcc, 0, v11, vcc
	global_load_dwordx4 v[172:175], v[10:11], off offset:768
	global_load_dwordx4 v[176:179], v[10:11], off offset:1792
	global_load_dwordx4 v[180:183], v[10:11], off offset:2816
	global_load_dwordx4 v[184:187], v[10:11], off offset:3840
	v_add_co_u32_e32 v10, vcc, 0x80000, v10
	s_nop 1
	v_addc_co_u32_e32 v11, vcc, 0, v11, vcc
	global_load_dwordx4 v[188:191], v[10:11], off offset:768
	global_load_dwordx4 v[192:195], v[10:11], off offset:1792
	global_load_dwordx4 v[196:199], v[10:11], off offset:2816
	global_load_dwordx4 v[200:203], v[10:11], off offset:3840
	v_add_co_u32_e32 v10, vcc, 0x80000, v10
	s_nop 1
	v_addc_co_u32_e32 v11, vcc, 0, v11, vcc
	global_load_dwordx4 v[204:207], v[10:11], off offset:768
	global_load_dwordx4 v[208:211], v[10:11], off offset:1792
	global_load_dwordx4 v[212:215], v[10:11], off offset:2816
	global_load_dwordx4 v[216:219], v[10:11], off offset:3840
	v_add_co_u32_e32 v10, vcc, 0x80000, v10
	s_nop 1
	v_addc_co_u32_e32 v11, vcc, 0, v11, vcc
	global_load_dwordx4 v[220:223], v[10:11], off offset:768
	global_load_dwordx4 v[224:227], v[10:11], off offset:1792
	global_load_dwordx4 v[228:231], v[10:11], off offset:2816
	global_load_dwordx4 v[232:235], v[10:11], off offset:3840
	s_waitcnt vmcnt(0)
	v_lshlrev_b32_e32 v12, 16, v100
	v_and_b32_e32 v13, 0xffff0000, v100
	v_lshlrev_b32_e32 v14, 16, v101
	v_and_b32_e32 v15, 0xffff0000, v101
	v_pk_add_f32 v[110:111], v[110:111], v[14:15]
	v_pk_add_f32 v[108:109], v[108:109], v[12:13]
	v_pk_add_f32 v[110:111], v[126:127], v[110:111]
	v_pk_add_f32 v[108:109], v[124:125], v[108:109]
	v_pk_add_f32 v[110:111], v[142:143], v[110:111]
	v_pk_add_f32 v[108:109], v[140:141], v[108:109]
	v_pk_add_f32 v[110:111], v[158:159], v[110:111]
	v_pk_add_f32 v[108:109], v[156:157], v[108:109]
	v_pk_add_f32 v[110:111], v[174:175], v[110:111]
	v_pk_add_f32 v[108:109], v[172:173], v[108:109]
	v_pk_add_f32 v[110:111], v[190:191], v[110:111]
	v_pk_add_f32 v[108:109], v[188:189], v[108:109]
	v_pk_add_f32 v[110:111], v[206:207], v[110:111]
	v_pk_add_f32 v[108:109], v[204:205], v[108:109]
	v_pk_add_f32 v[110:111], v[222:223], v[110:111]
	v_pk_add_f32 v[108:109], v[220:221], v[108:109]
	v_mul_f32_e32 v16, v109, v109
	v_mul_f32_e32 v17, v111, v111
	v_fmac_f32_e32 v16, v108, v108
	v_fmac_f32_e32 v17, v110, v110
	v_add_f32_e32 v6, v16, v17
	v_cvt_pk_bf16_f32 v18, v108, v109
	v_cvt_pk_bf16_f32 v19, v110, v111
	global_store_dwordx2 v[4:5], v[18:19], off offset:768
	v_lshlrev_b32_e32 v12, 16, v102
	v_and_b32_e32 v13, 0xffff0000, v102
	v_lshlrev_b32_e32 v14, 16, v103
	v_and_b32_e32 v15, 0xffff0000, v103
	v_pk_add_f32 v[114:115], v[114:115], v[14:15]
	v_pk_add_f32 v[112:113], v[112:113], v[12:13]
	v_pk_add_f32 v[114:115], v[130:131], v[114:115]
	v_pk_add_f32 v[112:113], v[128:129], v[112:113]
	v_pk_add_f32 v[114:115], v[146:147], v[114:115]
	v_pk_add_f32 v[112:113], v[144:145], v[112:113]
	v_pk_add_f32 v[114:115], v[162:163], v[114:115]
	v_pk_add_f32 v[112:113], v[160:161], v[112:113]
	v_pk_add_f32 v[114:115], v[178:179], v[114:115]
	v_pk_add_f32 v[112:113], v[176:177], v[112:113]
	v_pk_add_f32 v[114:115], v[194:195], v[114:115]
	v_pk_add_f32 v[112:113], v[192:193], v[112:113]
	v_pk_add_f32 v[114:115], v[210:211], v[114:115]
	v_pk_add_f32 v[112:113], v[208:209], v[112:113]
	v_pk_add_f32 v[114:115], v[226:227], v[114:115]
	v_pk_add_f32 v[112:113], v[224:225], v[112:113]
	v_mul_f32_e32 v16, v113, v113
	v_mul_f32_e32 v17, v115, v115
	v_fmac_f32_e32 v16, v112, v112
	v_fmac_f32_e32 v17, v114, v114
	v_add_f32_e32 v16, v16, v17
	v_add_f32_e32 v6, v6, v16
	v_cvt_pk_bf16_f32 v18, v112, v113
	v_cvt_pk_bf16_f32 v19, v114, v115
	global_store_dwordx2 v[4:5], v[18:19], off offset:1280
	v_lshlrev_b32_e32 v12, 16, v104
	v_and_b32_e32 v13, 0xffff0000, v104
	v_lshlrev_b32_e32 v14, 16, v105
	v_and_b32_e32 v15, 0xffff0000, v105
	v_pk_add_f32 v[118:119], v[118:119], v[14:15]
	v_pk_add_f32 v[116:117], v[116:117], v[12:13]
	v_pk_add_f32 v[118:119], v[134:135], v[118:119]
	v_pk_add_f32 v[116:117], v[132:133], v[116:117]
	v_pk_add_f32 v[118:119], v[150:151], v[118:119]
	v_pk_add_f32 v[116:117], v[148:149], v[116:117]
	v_pk_add_f32 v[118:119], v[166:167], v[118:119]
	v_pk_add_f32 v[116:117], v[164:165], v[116:117]
	v_pk_add_f32 v[118:119], v[182:183], v[118:119]
	v_pk_add_f32 v[116:117], v[180:181], v[116:117]
	v_pk_add_f32 v[118:119], v[198:199], v[118:119]
	v_pk_add_f32 v[116:117], v[196:197], v[116:117]
	v_pk_add_f32 v[118:119], v[214:215], v[118:119]
	v_pk_add_f32 v[116:117], v[212:213], v[116:117]
	v_pk_add_f32 v[118:119], v[230:231], v[118:119]
	v_pk_add_f32 v[116:117], v[228:229], v[116:117]
	v_mul_f32_e32 v16, v117, v117
	v_mul_f32_e32 v17, v119, v119
	v_fmac_f32_e32 v16, v116, v116
	v_fmac_f32_e32 v17, v118, v118
	v_add_f32_e32 v16, v16, v17
	v_add_f32_e32 v6, v6, v16
	v_cvt_pk_bf16_f32 v18, v116, v117
	v_cvt_pk_bf16_f32 v19, v118, v119
	global_store_dwordx2 v[4:5], v[18:19], off offset:1792
	v_lshlrev_b32_e32 v12, 16, v106
	v_and_b32_e32 v13, 0xffff0000, v106
	v_lshlrev_b32_e32 v14, 16, v107
	v_and_b32_e32 v15, 0xffff0000, v107
	v_pk_add_f32 v[122:123], v[122:123], v[14:15]
	v_pk_add_f32 v[120:121], v[120:121], v[12:13]
	v_pk_add_f32 v[122:123], v[138:139], v[122:123]
	v_pk_add_f32 v[120:121], v[136:137], v[120:121]
	v_pk_add_f32 v[122:123], v[154:155], v[122:123]
	v_pk_add_f32 v[120:121], v[152:153], v[120:121]
	v_pk_add_f32 v[122:123], v[170:171], v[122:123]
	v_pk_add_f32 v[120:121], v[168:169], v[120:121]
	v_pk_add_f32 v[122:123], v[186:187], v[122:123]
	v_pk_add_f32 v[120:121], v[184:185], v[120:121]
	v_pk_add_f32 v[122:123], v[202:203], v[122:123]
	v_pk_add_f32 v[120:121], v[200:201], v[120:121]
	v_pk_add_f32 v[122:123], v[218:219], v[122:123]
	v_pk_add_f32 v[120:121], v[216:217], v[120:121]
	v_pk_add_f32 v[122:123], v[234:235], v[122:123]
	v_pk_add_f32 v[120:121], v[232:233], v[120:121]
	v_mul_f32_e32 v16, v121, v121
	v_mul_f32_e32 v17, v123, v123
	v_fmac_f32_e32 v16, v120, v120
	v_fmac_f32_e32 v17, v122, v122
	v_add_f32_e32 v16, v16, v17
	v_add_f32_e32 v6, v6, v16
	v_cvt_pk_bf16_f32 v18, v120, v121
	v_cvt_pk_bf16_f32 v19, v122, v123
	global_store_dwordx2 v[4:5], v[18:19], off offset:2304
	ds_bpermute_b32 v7, v22, v6
	s_waitcnt lgkmcnt(0)
	v_add_f32_e32 v6, v6, v7
	ds_bpermute_b32 v7, v23, v6
	s_waitcnt lgkmcnt(0)
	v_add_f32_e32 v6, v6, v7
	ds_bpermute_b32 v7, v24, v6
	s_waitcnt lgkmcnt(0)
	v_add_f32_e32 v6, v6, v7
	ds_bpermute_b32 v7, v25, v6
	s_waitcnt lgkmcnt(0)
	v_add_f32_e32 v6, v6, v7
	ds_bpermute_b32 v7, v26, v6
	s_waitcnt lgkmcnt(0)
	v_add_f32_e32 v6, v6, v7
	ds_bpermute_b32 v7, v27, v6
	s_and_saveexec_b64 s[14:15], s[6:7]
	s_cbranch_execz .LBB0_486
	s_add_u32 s16, s82, s2
	s_addc_u32 s17, s83, s3
	s_waitcnt lgkmcnt(0)
	v_add_f32_e32 v4, v6, v7
	global_store_dword v21, v4, s[16:17]
	s_branch .LBB0_486

.LBB0_788:
	v_lshl_add_u64 v[4:5], s[82:83], 0, v[2:3]
	v_add_co_u32_e32 v4, vcc, 0xba67000, v4
	v_lshl_add_u64 v[8:9], s[82:83], 0, v[0:1]
	s_nop 0
	v_addc_co_u32_e32 v5, vcc, 0, v5, vcc
	v_add_co_u32_e32 v8, vcc, 0x34a77000, v8
	s_waitcnt lgkmcnt(0)
	s_nop 0
	v_addc_co_u32_e32 v9, vcc, 0, v9, vcc
	global_load_dwordx2 v[100:101], v[4:5], off offset:768
	global_load_dwordx2 v[102:103], v[4:5], off offset:1280
	v_mov_b32_e32 v10, v8
	v_mov_b32_e32 v11, v9
	global_load_dwordx4 v[104:107], v[10:11], off offset:768
	global_load_dwordx4 v[108:111], v[10:11], off offset:1792
	v_add_co_u32_e32 v10, vcc, 0x80000, v10
	s_nop 1
	v_addc_co_u32_e32 v11, vcc, 0, v11, vcc
	global_load_dwordx4 v[112:115], v[10:11], off offset:768
	global_load_dwordx4 v[116:119], v[10:11], off offset:1792
	v_add_co_u32_e32 v10, vcc, 0x80000, v10
	s_nop 1
	v_addc_co_u32_e32 v11, vcc, 0, v11, vcc
	global_load_dwordx4 v[120:123], v[10:11], off offset:768
	global_load_dwordx4 v[124:127], v[10:11], off offset:1792
	v_add_co_u32_e32 v10, vcc, 0x80000, v10
	s_nop 1
	v_addc_co_u32_e32 v11, vcc, 0, v11, vcc
	global_load_dwordx4 v[128:131], v[10:11], off offset:768
	global_load_dwordx4 v[132:135], v[10:11], off offset:1792
	v_add_co_u32_e32 v10, vcc, 0x80000, v10
	s_nop 1
	v_addc_co_u32_e32 v11, vcc, 0, v11, vcc
	global_load_dwordx4 v[136:139], v[10:11], off offset:768
	global_load_dwordx4 v[140:143], v[10:11], off offset:1792
	v_add_co_u32_e32 v10, vcc, 0x80000, v10
	s_nop 1
	v_addc_co_u32_e32 v11, vcc, 0, v11, vcc
	global_load_dwordx4 v[144:147], v[10:11], off offset:768
	global_load_dwordx4 v[148:151], v[10:11], off offset:1792
	v_add_co_u32_e32 v10, vcc, 0x80000, v10
	s_nop 1
	v_addc_co_u32_e32 v11, vcc, 0, v11, vcc
	global_load_dwordx4 v[152:155], v[10:11], off offset:768
	global_load_dwordx4 v[156:159], v[10:11], off offset:1792
	v_add_co_u32_e32 v10, vcc, 0x80000, v10
	s_nop 1
	v_addc_co_u32_e32 v11, vcc, 0, v11, vcc
	global_load_dwordx4 v[160:163], v[10:11], off offset:768
	global_load_dwordx4 v[164:167], v[10:11], off offset:1792
	v_add_co_u32_e32 v10, vcc, 0x80000, v10
	s_nop 1
	v_addc_co_u32_e32 v11, vcc, 0, v11, vcc
	global_load_dwordx4 v[168:171], v[10:11], off offset:768
	global_load_dwordx4 v[172:175], v[10:11], off offset:1792
	v_add_co_u32_e32 v10, vcc, 0x80000, v10
	s_nop 1
	v_addc_co_u32_e32 v11, vcc, 0, v11, vcc
	global_load_dwordx4 v[176:179], v[10:11], off offset:768
	global_load_dwordx4 v[180:183], v[10:11], off offset:1792
	v_add_co_u32_e32 v10, vcc, 0x80000, v10
	s_nop 1
	v_addc_co_u32_e32 v11, vcc, 0, v11, vcc
	global_load_dwordx4 v[184:187], v[10:11], off offset:768
	global_load_dwordx4 v[188:191], v[10:11], off offset:1792
	s_waitcnt vmcnt(0)
	v_lshlrev_b32_e32 v12, 16, v100
	v_and_b32_e32 v13, 0xffff0000, v100
	v_lshlrev_b32_e32 v14, 16, v101
	v_and_b32_e32 v15, 0xffff0000, v101
	v_pk_add_f32 v[106:107], v[106:107], v[14:15]
	v_pk_add_f32 v[104:105], v[104:105], v[12:13]
	v_pk_add_f32 v[106:107], v[114:115], v[106:107]
	v_pk_add_f32 v[104:105], v[112:113], v[104:105]
	v_pk_add_f32 v[106:107], v[122:123], v[106:107]
	v_pk_add_f32 v[104:105], v[120:121], v[104:105]
	v_pk_add_f32 v[106:107], v[130:131], v[106:107]
	v_pk_add_f32 v[104:105], v[128:129], v[104:105]
	v_pk_add_f32 v[106:107], v[138:139], v[106:107]
	v_pk_add_f32 v[104:105], v[136:137], v[104:105]
	v_pk_add_f32 v[106:107], v[146:147], v[106:107]
	v_pk_add_f32 v[104:105], v[144:145], v[104:105]
	v_pk_add_f32 v[106:107], v[154:155], v[106:107]
	v_pk_add_f32 v[104:105], v[152:153], v[104:105]
	v_pk_add_f32 v[106:107], v[162:163], v[106:107]
	v_pk_add_f32 v[104:105], v[160:161], v[104:105]
	v_pk_add_f32 v[106:107], v[170:171], v[106:107]
	v_pk_add_f32 v[104:105], v[168:169], v[104:105]
	v_pk_add_f32 v[106:107], v[178:179], v[106:107]
	v_pk_add_f32 v[104:105], v[176:177], v[104:105]
	v_pk_add_f32 v[106:107], v[186:187], v[106:107]
	v_pk_add_f32 v[104:105], v[184:185], v[104:105]
	v_mul_f32_e32 v16, v105, v105
	v_mul_f32_e32 v17, v107, v107
	v_fmac_f32_e32 v16, v104, v104
	v_fmac_f32_e32 v17, v106, v106
	v_add_f32_e32 v6, v16, v17
	v_cvt_pk_bf16_f32 v18, v104, v105
	v_cvt_pk_bf16_f32 v19, v106, v107
	global_store_dwordx2 v[4:5], v[18:19], off offset:768
	v_lshlrev_b32_e32 v12, 16, v102
	v_and_b32_e32 v13, 0xffff0000, v102
	v_lshlrev_b32_e32 v14, 16, v103
	v_and_b32_e32 v15, 0xffff0000, v103
	v_pk_add_f32 v[110:111], v[110:111], v[14:15]
	v_pk_add_f32 v[108:109], v[108:109], v[12:13]
	v_pk_add_f32 v[110:111], v[118:119], v[110:111]
	v_pk_add_f32 v[108:109], v[116:117], v[108:109]
	v_pk_add_f32 v[110:111], v[126:127], v[110:111]
	v_pk_add_f32 v[108:109], v[124:125], v[108:109]
	v_pk_add_f32 v[110:111], v[134:135], v[110:111]
	v_pk_add_f32 v[108:109], v[132:133], v[108:109]
	v_pk_add_f32 v[110:111], v[142:143], v[110:111]
	v_pk_add_f32 v[108:109], v[140:141], v[108:109]
	v_pk_add_f32 v[110:111], v[150:151], v[110:111]
	v_pk_add_f32 v[108:109], v[148:149], v[108:109]
	v_pk_add_f32 v[110:111], v[158:159], v[110:111]
	v_pk_add_f32 v[108:109], v[156:157], v[108:109]
	v_pk_add_f32 v[110:111], v[166:167], v[110:111]
	v_pk_add_f32 v[108:109], v[164:165], v[108:109]
	v_pk_add_f32 v[110:111], v[174:175], v[110:111]
	v_pk_add_f32 v[108:109], v[172:173], v[108:109]
	v_pk_add_f32 v[110:111], v[182:183], v[110:111]
	v_pk_add_f32 v[108:109], v[180:181], v[108:109]
	v_pk_add_f32 v[110:111], v[190:191], v[110:111]
	v_pk_add_f32 v[108:109], v[188:189], v[108:109]
	v_mul_f32_e32 v16, v109, v109
	v_mul_f32_e32 v17, v111, v111
	v_fmac_f32_e32 v16, v108, v108
	v_fmac_f32_e32 v17, v110, v110
	v_add_f32_e32 v16, v16, v17
	v_add_f32_e32 v6, v6, v16
	v_cvt_pk_bf16_f32 v18, v108, v109
	v_cvt_pk_bf16_f32 v19, v110, v111
	global_store_dwordx2 v[4:5], v[18:19], off offset:1280
	global_load_dwordx2 v[100:101], v[4:5], off offset:1792
	global_load_dwordx2 v[102:103], v[4:5], off offset:2304
	v_mov_b32_e32 v10, v8
	v_mov_b32_e32 v11, v9
	global_load_dwordx4 v[104:107], v[10:11], off offset:2816
	global_load_dwordx4 v[108:111], v[10:11], off offset:3840
	v_add_co_u32_e32 v10, vcc, 0x80000, v10
	s_nop 1
	v_addc_co_u32_e32 v11, vcc, 0, v11, vcc
	global_load_dwordx4 v[112:115], v[10:11], off offset:2816
	global_load_dwordx4 v[116:119], v[10:11], off offset:3840
	v_add_co_u32_e32 v10, vcc, 0x80000, v10
	s_nop 1
	v_addc_co_u32_e32 v11, vcc, 0, v11, vcc
	global_load_dwordx4 v[120:123], v[10:11], off offset:2816
	global_load_dwordx4 v[124:127], v[10:11], off offset:3840
	v_add_co_u32_e32 v10, vcc, 0x80000, v10
	s_nop 1
	v_addc_co_u32_e32 v11, vcc, 0, v11, vcc
	global_load_dwordx4 v[128:131], v[10:11], off offset:2816
	global_load_dwordx4 v[132:135], v[10:11], off offset:3840
	v_add_co_u32_e32 v10, vcc, 0x80000, v10
	s_nop 1
	v_addc_co_u32_e32 v11, vcc, 0, v11, vcc
	global_load_dwordx4 v[136:139], v[10:11], off offset:2816
	global_load_dwordx4 v[140:143], v[10:11], off offset:3840
	v_add_co_u32_e32 v10, vcc, 0x80000, v10
	s_nop 1
	v_addc_co_u32_e32 v11, vcc, 0, v11, vcc
	global_load_dwordx4 v[144:147], v[10:11], off offset:2816
	global_load_dwordx4 v[148:151], v[10:11], off offset:3840
	v_add_co_u32_e32 v10, vcc, 0x80000, v10
	s_nop 1
	v_addc_co_u32_e32 v11, vcc, 0, v11, vcc
	global_load_dwordx4 v[152:155], v[10:11], off offset:2816
	global_load_dwordx4 v[156:159], v[10:11], off offset:3840
	v_add_co_u32_e32 v10, vcc, 0x80000, v10
	s_nop 1
	v_addc_co_u32_e32 v11, vcc, 0, v11, vcc
	global_load_dwordx4 v[160:163], v[10:11], off offset:2816
	global_load_dwordx4 v[164:167], v[10:11], off offset:3840
	v_add_co_u32_e32 v10, vcc, 0x80000, v10
	s_nop 1
	v_addc_co_u32_e32 v11, vcc, 0, v11, vcc
	global_load_dwordx4 v[168:171], v[10:11], off offset:2816
	global_load_dwordx4 v[172:175], v[10:11], off offset:3840
	v_add_co_u32_e32 v10, vcc, 0x80000, v10
	s_nop 1
	v_addc_co_u32_e32 v11, vcc, 0, v11, vcc
	global_load_dwordx4 v[176:179], v[10:11], off offset:2816
	global_load_dwordx4 v[180:183], v[10:11], off offset:3840
	v_add_co_u32_e32 v10, vcc, 0x80000, v10
	s_nop 1
	v_addc_co_u32_e32 v11, vcc, 0, v11, vcc
	global_load_dwordx4 v[184:187], v[10:11], off offset:2816
	global_load_dwordx4 v[188:191], v[10:11], off offset:3840
	s_waitcnt vmcnt(0)
	v_lshlrev_b32_e32 v12, 16, v100
	v_and_b32_e32 v13, 0xffff0000, v100
	v_lshlrev_b32_e32 v14, 16, v101
	v_and_b32_e32 v15, 0xffff0000, v101
	v_pk_add_f32 v[106:107], v[106:107], v[14:15]
	v_pk_add_f32 v[104:105], v[104:105], v[12:13]
	v_pk_add_f32 v[106:107], v[114:115], v[106:107]
	v_pk_add_f32 v[104:105], v[112:113], v[104:105]
	v_pk_add_f32 v[106:107], v[122:123], v[106:107]
	v_pk_add_f32 v[104:105], v[120:121], v[104:105]
	v_pk_add_f32 v[106:107], v[130:131], v[106:107]
	v_pk_add_f32 v[104:105], v[128:129], v[104:105]
	v_pk_add_f32 v[106:107], v[138:139], v[106:107]
	v_pk_add_f32 v[104:105], v[136:137], v[104:105]
	v_pk_add_f32 v[106:107], v[146:147], v[106:107]
	v_pk_add_f32 v[104:105], v[144:145], v[104:105]
	v_pk_add_f32 v[106:107], v[154:155], v[106:107]
	v_pk_add_f32 v[104:105], v[152:153], v[104:105]
	v_pk_add_f32 v[106:107], v[162:163], v[106:107]
	v_pk_add_f32 v[104:105], v[160:161], v[104:105]
	v_pk_add_f32 v[106:107], v[170:171], v[106:107]
	v_pk_add_f32 v[104:105], v[168:169], v[104:105]
	v_pk_add_f32 v[106:107], v[178:179], v[106:107]
	v_pk_add_f32 v[104:105], v[176:177], v[104:105]
	v_pk_add_f32 v[106:107], v[186:187], v[106:107]
	v_pk_add_f32 v[104:105], v[184:185], v[104:105]
	v_mul_f32_e32 v16, v105, v105
	v_mul_f32_e32 v17, v107, v107
	v_fmac_f32_e32 v16, v104, v104
	v_fmac_f32_e32 v17, v106, v106
	v_add_f32_e32 v16, v16, v17
	v_add_f32_e32 v6, v6, v16
	v_cvt_pk_bf16_f32 v18, v104, v105
	v_cvt_pk_bf16_f32 v19, v106, v107
	global_store_dwordx2 v[4:5], v[18:19], off offset:1792
	v_lshlrev_b32_e32 v12, 16, v102
	v_and_b32_e32 v13, 0xffff0000, v102
	v_lshlrev_b32_e32 v14, 16, v103
	v_and_b32_e32 v15, 0xffff0000, v103
	v_pk_add_f32 v[110:111], v[110:111], v[14:15]
	v_pk_add_f32 v[108:109], v[108:109], v[12:13]
	v_pk_add_f32 v[110:111], v[118:119], v[110:111]
	v_pk_add_f32 v[108:109], v[116:117], v[108:109]
	v_pk_add_f32 v[110:111], v[126:127], v[110:111]
	v_pk_add_f32 v[108:109], v[124:125], v[108:109]
	v_pk_add_f32 v[110:111], v[134:135], v[110:111]
	v_pk_add_f32 v[108:109], v[132:133], v[108:109]
	v_pk_add_f32 v[110:111], v[142:143], v[110:111]
	v_pk_add_f32 v[108:109], v[140:141], v[108:109]
	v_pk_add_f32 v[110:111], v[150:151], v[110:111]
	v_pk_add_f32 v[108:109], v[148:149], v[108:109]
	v_pk_add_f32 v[110:111], v[158:159], v[110:111]
	v_pk_add_f32 v[108:109], v[156:157], v[108:109]
	v_pk_add_f32 v[110:111], v[166:167], v[110:111]
	v_pk_add_f32 v[108:109], v[164:165], v[108:109]
	v_pk_add_f32 v[110:111], v[174:175], v[110:111]
	v_pk_add_f32 v[108:109], v[172:173], v[108:109]
	v_pk_add_f32 v[110:111], v[182:183], v[110:111]
	v_pk_add_f32 v[108:109], v[180:181], v[108:109]
	v_pk_add_f32 v[110:111], v[190:191], v[110:111]
	v_pk_add_f32 v[108:109], v[188:189], v[108:109]
	v_mul_f32_e32 v16, v109, v109
	v_mul_f32_e32 v17, v111, v111
	v_fmac_f32_e32 v16, v108, v108
	v_fmac_f32_e32 v17, v110, v110
	v_add_f32_e32 v16, v16, v17
	v_add_f32_e32 v6, v6, v16
	v_cvt_pk_bf16_f32 v18, v108, v109
	v_cvt_pk_bf16_f32 v19, v110, v111
	global_store_dwordx2 v[4:5], v[18:19], off offset:2304
	ds_bpermute_b32 v7, v34, v6
	s_waitcnt lgkmcnt(0)
	v_add_f32_e32 v6, v6, v7
	ds_bpermute_b32 v7, v35, v6
	s_waitcnt lgkmcnt(0)
	v_add_f32_e32 v6, v6, v7
	ds_bpermute_b32 v7, v36, v6
	s_waitcnt lgkmcnt(0)
	v_add_f32_e32 v6, v6, v7
	ds_bpermute_b32 v7, v37, v6
	s_waitcnt lgkmcnt(0)
	v_add_f32_e32 v6, v6, v7
	ds_bpermute_b32 v7, v38, v6
	s_waitcnt lgkmcnt(0)
	v_add_f32_e32 v6, v6, v7
	ds_bpermute_b32 v7, v39, v6
	s_and_saveexec_b64 s[14:15], s[12:13]
	s_cbranch_execz .LBB0_787
	s_add_u32 s16, s82, s2
	s_waitcnt lgkmcnt(0)
	v_add_f32_e32 v4, v6, v7
	s_addc_u32 s17, s83, s3
	global_store_dword v33, v4, s[16:17]
	s_branch .LBB0_787

.LBB0_1260:
	v_lshl_add_u64 v[4:5], s[82:83], 0, v[2:3]
	v_add_co_u32_e32 v4, vcc, 0xba67000, v4
	v_lshl_add_u64 v[8:9], s[82:83], 0, v[0:1]
	s_nop 0
	v_addc_co_u32_e32 v5, vcc, 0, v5, vcc
	v_add_co_u32_e32 v8, vcc, 0x34a77000, v8
	s_waitcnt lgkmcnt(0)
	s_nop 0
	v_addc_co_u32_e32 v9, vcc, 0, v9, vcc
	global_load_dwordx2 v[100:101], v[4:5], off offset:768
	global_load_dwordx2 v[102:103], v[4:5], off offset:1280
	global_load_dwordx2 v[104:105], v[4:5], off offset:1792
	global_load_dwordx2 v[106:107], v[4:5], off offset:2304
	v_mov_b32_e32 v10, v8
	v_mov_b32_e32 v11, v9
	global_load_dwordx4 v[108:111], v[10:11], off offset:768
	global_load_dwordx4 v[112:115], v[10:11], off offset:1792
	global_load_dwordx4 v[116:119], v[10:11], off offset:2816
	global_load_dwordx4 v[120:123], v[10:11], off offset:3840
	v_add_co_u32_e32 v10, vcc, 0x80000, v10
	s_nop 1
	v_addc_co_u32_e32 v11, vcc, 0, v11, vcc
	global_load_dwordx4 v[124:127], v[10:11], off offset:768
	global_load_dwordx4 v[128:131], v[10:11], off offset:1792
	global_load_dwordx4 v[132:135], v[10:11], off offset:2816
	global_load_dwordx4 v[136:139], v[10:11], off offset:3840
	v_add_co_u32_e32 v10, vcc, 0x80000, v10
	s_nop 1
	v_addc_co_u32_e32 v11, vcc, 0, v11, vcc
	global_load_dwordx4 v[140:143], v[10:11], off offset:768
	global_load_dwordx4 v[144:147], v[10:11], off offset:1792
	global_load_dwordx4 v[148:151], v[10:11], off offset:2816
	global_load_dwordx4 v[152:155], v[10:11], off offset:3840
	v_add_co_u32_e32 v10, vcc, 0x80000, v10
	s_nop 1
	v_addc_co_u32_e32 v11, vcc, 0, v11, vcc
	global_load_dwordx4 v[156:159], v[10:11], off offset:768
	global_load_dwordx4 v[160:163], v[10:11], off offset:1792
	global_load_dwordx4 v[164:167], v[10:11], off offset:2816
	global_load_dwordx4 v[168:171], v[10:11], off offset:3840
	v_add_co_u32_e32 v10, vcc, 0x80000, v10
	s_nop 1
	v_addc_co_u32_e32 v11, vcc, 0, v11, vcc
	global_load_dwordx4 v[172:175], v[10:11], off offset:768
	global_load_dwordx4 v[176:179], v[10:11], off offset:1792
	global_load_dwordx4 v[180:183], v[10:11], off offset:2816
	global_load_dwordx4 v[184:187], v[10:11], off offset:3840
	v_add_co_u32_e32 v10, vcc, 0x80000, v10
	s_nop 1
	v_addc_co_u32_e32 v11, vcc, 0, v11, vcc
	global_load_dwordx4 v[188:191], v[10:11], off offset:768
	global_load_dwordx4 v[192:195], v[10:11], off offset:1792
	global_load_dwordx4 v[196:199], v[10:11], off offset:2816
	global_load_dwordx4 v[200:203], v[10:11], off offset:3840
	v_add_co_u32_e32 v10, vcc, 0x80000, v10
	s_nop 1
	v_addc_co_u32_e32 v11, vcc, 0, v11, vcc
	global_load_dwordx4 v[204:207], v[10:11], off offset:768
	global_load_dwordx4 v[208:211], v[10:11], off offset:1792
	global_load_dwordx4 v[212:215], v[10:11], off offset:2816
	global_load_dwordx4 v[216:219], v[10:11], off offset:3840
	v_add_co_u32_e32 v10, vcc, 0x80000, v10
	s_nop 1
	v_addc_co_u32_e32 v11, vcc, 0, v11, vcc
	global_load_dwordx4 v[220:223], v[10:11], off offset:768
	global_load_dwordx4 v[224:227], v[10:11], off offset:1792
	global_load_dwordx4 v[228:231], v[10:11], off offset:2816
	global_load_dwordx4 v[232:235], v[10:11], off offset:3840
	s_waitcnt vmcnt(0)
	v_lshlrev_b32_e32 v12, 16, v100
	v_and_b32_e32 v13, 0xffff0000, v100
	v_lshlrev_b32_e32 v14, 16, v101
	v_and_b32_e32 v15, 0xffff0000, v101
	v_pk_add_f32 v[110:111], v[110:111], v[14:15]
	v_pk_add_f32 v[108:109], v[108:109], v[12:13]
	v_pk_add_f32 v[110:111], v[126:127], v[110:111]
	v_pk_add_f32 v[108:109], v[124:125], v[108:109]
	v_pk_add_f32 v[110:111], v[142:143], v[110:111]
	v_pk_add_f32 v[108:109], v[140:141], v[108:109]
	v_pk_add_f32 v[110:111], v[158:159], v[110:111]
	v_pk_add_f32 v[108:109], v[156:157], v[108:109]
	v_pk_add_f32 v[110:111], v[174:175], v[110:111]
	v_pk_add_f32 v[108:109], v[172:173], v[108:109]
	v_pk_add_f32 v[110:111], v[190:191], v[110:111]
	v_pk_add_f32 v[108:109], v[188:189], v[108:109]
	v_pk_add_f32 v[110:111], v[206:207], v[110:111]
	v_pk_add_f32 v[108:109], v[204:205], v[108:109]
	v_pk_add_f32 v[110:111], v[222:223], v[110:111]
	v_pk_add_f32 v[108:109], v[220:221], v[108:109]
	v_mul_f32_e32 v16, v109, v109
	v_mul_f32_e32 v17, v111, v111
	v_fmac_f32_e32 v16, v108, v108
	v_fmac_f32_e32 v17, v110, v110
	v_add_f32_e32 v6, v16, v17
	v_cvt_pk_bf16_f32 v18, v108, v109
	v_cvt_pk_bf16_f32 v19, v110, v111
	global_store_dwordx2 v[4:5], v[18:19], off offset:768
	v_lshlrev_b32_e32 v12, 16, v102
	v_and_b32_e32 v13, 0xffff0000, v102
	v_lshlrev_b32_e32 v14, 16, v103
	v_and_b32_e32 v15, 0xffff0000, v103
	v_pk_add_f32 v[114:115], v[114:115], v[14:15]
	v_pk_add_f32 v[112:113], v[112:113], v[12:13]
	v_pk_add_f32 v[114:115], v[130:131], v[114:115]
	v_pk_add_f32 v[112:113], v[128:129], v[112:113]
	v_pk_add_f32 v[114:115], v[146:147], v[114:115]
	v_pk_add_f32 v[112:113], v[144:145], v[112:113]
	v_pk_add_f32 v[114:115], v[162:163], v[114:115]
	v_pk_add_f32 v[112:113], v[160:161], v[112:113]
	v_pk_add_f32 v[114:115], v[178:179], v[114:115]
	v_pk_add_f32 v[112:113], v[176:177], v[112:113]
	v_pk_add_f32 v[114:115], v[194:195], v[114:115]
	v_pk_add_f32 v[112:113], v[192:193], v[112:113]
	v_pk_add_f32 v[114:115], v[210:211], v[114:115]
	v_pk_add_f32 v[112:113], v[208:209], v[112:113]
	v_pk_add_f32 v[114:115], v[226:227], v[114:115]
	v_pk_add_f32 v[112:113], v[224:225], v[112:113]
	v_mul_f32_e32 v16, v113, v113
	v_mul_f32_e32 v17, v115, v115
	v_fmac_f32_e32 v16, v112, v112
	v_fmac_f32_e32 v17, v114, v114
	v_add_f32_e32 v16, v16, v17
	v_add_f32_e32 v6, v6, v16
	v_cvt_pk_bf16_f32 v18, v112, v113
	v_cvt_pk_bf16_f32 v19, v114, v115
	global_store_dwordx2 v[4:5], v[18:19], off offset:1280
	v_lshlrev_b32_e32 v12, 16, v104
	v_and_b32_e32 v13, 0xffff0000, v104
	v_lshlrev_b32_e32 v14, 16, v105
	v_and_b32_e32 v15, 0xffff0000, v105
	v_pk_add_f32 v[118:119], v[118:119], v[14:15]
	v_pk_add_f32 v[116:117], v[116:117], v[12:13]
	v_pk_add_f32 v[118:119], v[134:135], v[118:119]
	v_pk_add_f32 v[116:117], v[132:133], v[116:117]
	v_pk_add_f32 v[118:119], v[150:151], v[118:119]
	v_pk_add_f32 v[116:117], v[148:149], v[116:117]
	v_pk_add_f32 v[118:119], v[166:167], v[118:119]
	v_pk_add_f32 v[116:117], v[164:165], v[116:117]
	v_pk_add_f32 v[118:119], v[182:183], v[118:119]
	v_pk_add_f32 v[116:117], v[180:181], v[116:117]
	v_pk_add_f32 v[118:119], v[198:199], v[118:119]
	v_pk_add_f32 v[116:117], v[196:197], v[116:117]
	v_pk_add_f32 v[118:119], v[214:215], v[118:119]
	v_pk_add_f32 v[116:117], v[212:213], v[116:117]
	v_pk_add_f32 v[118:119], v[230:231], v[118:119]
	v_pk_add_f32 v[116:117], v[228:229], v[116:117]
	v_mul_f32_e32 v16, v117, v117
	v_mul_f32_e32 v17, v119, v119
	v_fmac_f32_e32 v16, v116, v116
	v_fmac_f32_e32 v17, v118, v118
	v_add_f32_e32 v16, v16, v17
	v_add_f32_e32 v6, v6, v16
	v_cvt_pk_bf16_f32 v18, v116, v117
	v_cvt_pk_bf16_f32 v19, v118, v119
	global_store_dwordx2 v[4:5], v[18:19], off offset:1792
	v_lshlrev_b32_e32 v12, 16, v106
	v_and_b32_e32 v13, 0xffff0000, v106
	v_lshlrev_b32_e32 v14, 16, v107
	v_and_b32_e32 v15, 0xffff0000, v107
	v_pk_add_f32 v[122:123], v[122:123], v[14:15]
	v_pk_add_f32 v[120:121], v[120:121], v[12:13]
	v_pk_add_f32 v[122:123], v[138:139], v[122:123]
	v_pk_add_f32 v[120:121], v[136:137], v[120:121]
	v_pk_add_f32 v[122:123], v[154:155], v[122:123]
	v_pk_add_f32 v[120:121], v[152:153], v[120:121]
	v_pk_add_f32 v[122:123], v[170:171], v[122:123]
	v_pk_add_f32 v[120:121], v[168:169], v[120:121]
	v_pk_add_f32 v[122:123], v[186:187], v[122:123]
	v_pk_add_f32 v[120:121], v[184:185], v[120:121]
	v_pk_add_f32 v[122:123], v[202:203], v[122:123]
	v_pk_add_f32 v[120:121], v[200:201], v[120:121]
	v_pk_add_f32 v[122:123], v[218:219], v[122:123]
	v_pk_add_f32 v[120:121], v[216:217], v[120:121]
	v_pk_add_f32 v[122:123], v[234:235], v[122:123]
	v_pk_add_f32 v[120:121], v[232:233], v[120:121]
	v_mul_f32_e32 v16, v121, v121
	v_mul_f32_e32 v17, v123, v123
	v_fmac_f32_e32 v16, v120, v120
	v_fmac_f32_e32 v17, v122, v122
	v_add_f32_e32 v16, v16, v17
	v_add_f32_e32 v6, v6, v16
	v_cvt_pk_bf16_f32 v18, v120, v121
	v_cvt_pk_bf16_f32 v19, v122, v123
	global_store_dwordx2 v[4:5], v[18:19], off offset:2304
	ds_bpermute_b32 v7, v22, v6
	s_waitcnt lgkmcnt(0)
	v_add_f32_e32 v6, v6, v7
	ds_bpermute_b32 v7, v23, v6
	s_waitcnt lgkmcnt(0)
	v_add_f32_e32 v6, v6, v7
	ds_bpermute_b32 v7, v24, v6
	s_waitcnt lgkmcnt(0)
	v_add_f32_e32 v6, v6, v7
	ds_bpermute_b32 v7, v25, v6
	s_waitcnt lgkmcnt(0)
	v_add_f32_e32 v6, v6, v7
	ds_bpermute_b32 v7, v26, v6
	s_waitcnt lgkmcnt(0)
	v_add_f32_e32 v6, v6, v7
	ds_bpermute_b32 v7, v27, v6
	s_and_saveexec_b64 s[14:15], s[10:11]
	s_cbranch_execz .LBB0_1259
	s_add_u32 s16, s82, s2
	s_waitcnt lgkmcnt(0)
	v_add_f32_e32 v4, v6, v7
	s_addc_u32 s17, s83, s3
	global_store_dword v21, v4, s[16:17]
	s_branch .LBB0_1259

.LBB0_1596:
	v_lshl_add_u64 v[4:5], s[82:83], 0, v[2:3]
	v_add_co_u32_e32 v4, vcc, 0xba67000, v4
	v_lshl_add_u64 v[8:9], s[82:83], 0, v[0:1]
	s_nop 0
	v_addc_co_u32_e32 v5, vcc, 0, v5, vcc
	v_add_co_u32_e32 v8, vcc, 0x34a77000, v8
	s_waitcnt lgkmcnt(0)
	s_nop 0
	v_addc_co_u32_e32 v9, vcc, 0, v9, vcc
	global_load_dwordx2 v[100:101], v[4:5], off offset:768
	global_load_dwordx2 v[102:103], v[4:5], off offset:1280
	v_mov_b32_e32 v10, v8
	v_mov_b32_e32 v11, v9
	global_load_dwordx4 v[104:107], v[10:11], off offset:768
	global_load_dwordx4 v[108:111], v[10:11], off offset:1792
	v_add_co_u32_e32 v10, vcc, 0x80000, v10
	s_nop 1
	v_addc_co_u32_e32 v11, vcc, 0, v11, vcc
	global_load_dwordx4 v[112:115], v[10:11], off offset:768
	global_load_dwordx4 v[116:119], v[10:11], off offset:1792
	v_add_co_u32_e32 v10, vcc, 0x80000, v10
	s_nop 1
	v_addc_co_u32_e32 v11, vcc, 0, v11, vcc
	global_load_dwordx4 v[120:123], v[10:11], off offset:768
	global_load_dwordx4 v[124:127], v[10:11], off offset:1792
	v_add_co_u32_e32 v10, vcc, 0x80000, v10
	s_nop 1
	v_addc_co_u32_e32 v11, vcc, 0, v11, vcc
	global_load_dwordx4 v[128:131], v[10:11], off offset:768
	global_load_dwordx4 v[132:135], v[10:11], off offset:1792
	v_add_co_u32_e32 v10, vcc, 0x80000, v10
	s_nop 1
	v_addc_co_u32_e32 v11, vcc, 0, v11, vcc
	global_load_dwordx4 v[136:139], v[10:11], off offset:768
	global_load_dwordx4 v[140:143], v[10:11], off offset:1792
	v_add_co_u32_e32 v10, vcc, 0x80000, v10
	s_nop 1
	v_addc_co_u32_e32 v11, vcc, 0, v11, vcc
	global_load_dwordx4 v[144:147], v[10:11], off offset:768
	global_load_dwordx4 v[148:151], v[10:11], off offset:1792
	v_add_co_u32_e32 v10, vcc, 0x80000, v10
	s_nop 1
	v_addc_co_u32_e32 v11, vcc, 0, v11, vcc
	global_load_dwordx4 v[152:155], v[10:11], off offset:768
	global_load_dwordx4 v[156:159], v[10:11], off offset:1792
	v_add_co_u32_e32 v10, vcc, 0x80000, v10
	s_nop 1
	v_addc_co_u32_e32 v11, vcc, 0, v11, vcc
	global_load_dwordx4 v[160:163], v[10:11], off offset:768
	global_load_dwordx4 v[164:167], v[10:11], off offset:1792
	v_add_co_u32_e32 v10, vcc, 0x80000, v10
	s_nop 1
	v_addc_co_u32_e32 v11, vcc, 0, v11, vcc
	global_load_dwordx4 v[168:171], v[10:11], off offset:768
	global_load_dwordx4 v[172:175], v[10:11], off offset:1792
	v_add_co_u32_e32 v10, vcc, 0x80000, v10
	s_nop 1
	v_addc_co_u32_e32 v11, vcc, 0, v11, vcc
	global_load_dwordx4 v[176:179], v[10:11], off offset:768
	global_load_dwordx4 v[180:183], v[10:11], off offset:1792
	v_add_co_u32_e32 v10, vcc, 0x80000, v10
	s_nop 1
	v_addc_co_u32_e32 v11, vcc, 0, v11, vcc
	global_load_dwordx4 v[184:187], v[10:11], off offset:768
	global_load_dwordx4 v[188:191], v[10:11], off offset:1792
	s_waitcnt vmcnt(0)
	v_lshlrev_b32_e32 v12, 16, v100
	v_and_b32_e32 v13, 0xffff0000, v100
	v_lshlrev_b32_e32 v14, 16, v101
	v_and_b32_e32 v15, 0xffff0000, v101
	v_pk_add_f32 v[106:107], v[106:107], v[14:15]
	v_pk_add_f32 v[104:105], v[104:105], v[12:13]
	v_pk_add_f32 v[106:107], v[114:115], v[106:107]
	v_pk_add_f32 v[104:105], v[112:113], v[104:105]
	v_pk_add_f32 v[106:107], v[122:123], v[106:107]
	v_pk_add_f32 v[104:105], v[120:121], v[104:105]
	v_pk_add_f32 v[106:107], v[130:131], v[106:107]
	v_pk_add_f32 v[104:105], v[128:129], v[104:105]
	v_pk_add_f32 v[106:107], v[138:139], v[106:107]
	v_pk_add_f32 v[104:105], v[136:137], v[104:105]
	v_pk_add_f32 v[106:107], v[146:147], v[106:107]
	v_pk_add_f32 v[104:105], v[144:145], v[104:105]
	v_pk_add_f32 v[106:107], v[154:155], v[106:107]
	v_pk_add_f32 v[104:105], v[152:153], v[104:105]
	v_pk_add_f32 v[106:107], v[162:163], v[106:107]
	v_pk_add_f32 v[104:105], v[160:161], v[104:105]
	v_pk_add_f32 v[106:107], v[170:171], v[106:107]
	v_pk_add_f32 v[104:105], v[168:169], v[104:105]
	v_pk_add_f32 v[106:107], v[178:179], v[106:107]
	v_pk_add_f32 v[104:105], v[176:177], v[104:105]
	v_pk_add_f32 v[106:107], v[186:187], v[106:107]
	v_pk_add_f32 v[104:105], v[184:185], v[104:105]
	v_mul_f32_e32 v16, v105, v105
	v_mul_f32_e32 v17, v107, v107
	v_fmac_f32_e32 v16, v104, v104
	v_fmac_f32_e32 v17, v106, v106
	v_add_f32_e32 v6, v16, v17
	v_cvt_pk_bf16_f32 v18, v104, v105
	v_cvt_pk_bf16_f32 v19, v106, v107
	global_store_dwordx2 v[4:5], v[18:19], off offset:768
	v_lshlrev_b32_e32 v12, 16, v102
	v_and_b32_e32 v13, 0xffff0000, v102
	v_lshlrev_b32_e32 v14, 16, v103
	v_and_b32_e32 v15, 0xffff0000, v103
	v_pk_add_f32 v[110:111], v[110:111], v[14:15]
	v_pk_add_f32 v[108:109], v[108:109], v[12:13]
	v_pk_add_f32 v[110:111], v[118:119], v[110:111]
	v_pk_add_f32 v[108:109], v[116:117], v[108:109]
	v_pk_add_f32 v[110:111], v[126:127], v[110:111]
	v_pk_add_f32 v[108:109], v[124:125], v[108:109]
	v_pk_add_f32 v[110:111], v[134:135], v[110:111]
	v_pk_add_f32 v[108:109], v[132:133], v[108:109]
	v_pk_add_f32 v[110:111], v[142:143], v[110:111]
	v_pk_add_f32 v[108:109], v[140:141], v[108:109]
	v_pk_add_f32 v[110:111], v[150:151], v[110:111]
	v_pk_add_f32 v[108:109], v[148:149], v[108:109]
	v_pk_add_f32 v[110:111], v[158:159], v[110:111]
	v_pk_add_f32 v[108:109], v[156:157], v[108:109]
	v_pk_add_f32 v[110:111], v[166:167], v[110:111]
	v_pk_add_f32 v[108:109], v[164:165], v[108:109]
	v_pk_add_f32 v[110:111], v[174:175], v[110:111]
	v_pk_add_f32 v[108:109], v[172:173], v[108:109]
	v_pk_add_f32 v[110:111], v[182:183], v[110:111]
	v_pk_add_f32 v[108:109], v[180:181], v[108:109]
	v_pk_add_f32 v[110:111], v[190:191], v[110:111]
	v_pk_add_f32 v[108:109], v[188:189], v[108:109]
	v_mul_f32_e32 v16, v109, v109
	v_mul_f32_e32 v17, v111, v111
	v_fmac_f32_e32 v16, v108, v108
	v_fmac_f32_e32 v17, v110, v110
	v_add_f32_e32 v16, v16, v17
	v_add_f32_e32 v6, v6, v16
	v_cvt_pk_bf16_f32 v18, v108, v109
	v_cvt_pk_bf16_f32 v19, v110, v111
	global_store_dwordx2 v[4:5], v[18:19], off offset:1280
	global_load_dwordx2 v[100:101], v[4:5], off offset:1792
	global_load_dwordx2 v[102:103], v[4:5], off offset:2304
	v_mov_b32_e32 v10, v8
	v_mov_b32_e32 v11, v9
	global_load_dwordx4 v[104:107], v[10:11], off offset:2816
	global_load_dwordx4 v[108:111], v[10:11], off offset:3840
	v_add_co_u32_e32 v10, vcc, 0x80000, v10
	s_nop 1
	v_addc_co_u32_e32 v11, vcc, 0, v11, vcc
	global_load_dwordx4 v[112:115], v[10:11], off offset:2816
	global_load_dwordx4 v[116:119], v[10:11], off offset:3840
	v_add_co_u32_e32 v10, vcc, 0x80000, v10
	s_nop 1
	v_addc_co_u32_e32 v11, vcc, 0, v11, vcc
	global_load_dwordx4 v[120:123], v[10:11], off offset:2816
	global_load_dwordx4 v[124:127], v[10:11], off offset:3840
	v_add_co_u32_e32 v10, vcc, 0x80000, v10
	s_nop 1
	v_addc_co_u32_e32 v11, vcc, 0, v11, vcc
	global_load_dwordx4 v[128:131], v[10:11], off offset:2816
	global_load_dwordx4 v[132:135], v[10:11], off offset:3840
	v_add_co_u32_e32 v10, vcc, 0x80000, v10
	s_nop 1
	v_addc_co_u32_e32 v11, vcc, 0, v11, vcc
	global_load_dwordx4 v[136:139], v[10:11], off offset:2816
	global_load_dwordx4 v[140:143], v[10:11], off offset:3840
	v_add_co_u32_e32 v10, vcc, 0x80000, v10
	s_nop 1
	v_addc_co_u32_e32 v11, vcc, 0, v11, vcc
	global_load_dwordx4 v[144:147], v[10:11], off offset:2816
	global_load_dwordx4 v[148:151], v[10:11], off offset:3840
	v_add_co_u32_e32 v10, vcc, 0x80000, v10
	s_nop 1
	v_addc_co_u32_e32 v11, vcc, 0, v11, vcc
	global_load_dwordx4 v[152:155], v[10:11], off offset:2816
	global_load_dwordx4 v[156:159], v[10:11], off offset:3840
	v_add_co_u32_e32 v10, vcc, 0x80000, v10
	s_nop 1
	v_addc_co_u32_e32 v11, vcc, 0, v11, vcc
	global_load_dwordx4 v[160:163], v[10:11], off offset:2816
	global_load_dwordx4 v[164:167], v[10:11], off offset:3840
	v_add_co_u32_e32 v10, vcc, 0x80000, v10
	s_nop 1
	v_addc_co_u32_e32 v11, vcc, 0, v11, vcc
	global_load_dwordx4 v[168:171], v[10:11], off offset:2816
	global_load_dwordx4 v[172:175], v[10:11], off offset:3840
	v_add_co_u32_e32 v10, vcc, 0x80000, v10
	s_nop 1
	v_addc_co_u32_e32 v11, vcc, 0, v11, vcc
	global_load_dwordx4 v[176:179], v[10:11], off offset:2816
	global_load_dwordx4 v[180:183], v[10:11], off offset:3840
	v_add_co_u32_e32 v10, vcc, 0x80000, v10
	s_nop 1
	v_addc_co_u32_e32 v11, vcc, 0, v11, vcc
	global_load_dwordx4 v[184:187], v[10:11], off offset:2816
	global_load_dwordx4 v[188:191], v[10:11], off offset:3840
	s_waitcnt vmcnt(0)
	v_lshlrev_b32_e32 v12, 16, v100
	v_and_b32_e32 v13, 0xffff0000, v100
	v_lshlrev_b32_e32 v14, 16, v101
	v_and_b32_e32 v15, 0xffff0000, v101
	v_pk_add_f32 v[106:107], v[106:107], v[14:15]
	v_pk_add_f32 v[104:105], v[104:105], v[12:13]
	v_pk_add_f32 v[106:107], v[114:115], v[106:107]
	v_pk_add_f32 v[104:105], v[112:113], v[104:105]
	v_pk_add_f32 v[106:107], v[122:123], v[106:107]
	v_pk_add_f32 v[104:105], v[120:121], v[104:105]
	v_pk_add_f32 v[106:107], v[130:131], v[106:107]
	v_pk_add_f32 v[104:105], v[128:129], v[104:105]
	v_pk_add_f32 v[106:107], v[138:139], v[106:107]
	v_pk_add_f32 v[104:105], v[136:137], v[104:105]
	v_pk_add_f32 v[106:107], v[146:147], v[106:107]
	v_pk_add_f32 v[104:105], v[144:145], v[104:105]
	v_pk_add_f32 v[106:107], v[154:155], v[106:107]
	v_pk_add_f32 v[104:105], v[152:153], v[104:105]
	v_pk_add_f32 v[106:107], v[162:163], v[106:107]
	v_pk_add_f32 v[104:105], v[160:161], v[104:105]
	v_pk_add_f32 v[106:107], v[170:171], v[106:107]
	v_pk_add_f32 v[104:105], v[168:169], v[104:105]
	v_pk_add_f32 v[106:107], v[178:179], v[106:107]
	v_pk_add_f32 v[104:105], v[176:177], v[104:105]
	v_pk_add_f32 v[106:107], v[186:187], v[106:107]
	v_pk_add_f32 v[104:105], v[184:185], v[104:105]
	v_mul_f32_e32 v16, v105, v105
	v_mul_f32_e32 v17, v107, v107
	v_fmac_f32_e32 v16, v104, v104
	v_fmac_f32_e32 v17, v106, v106
	v_add_f32_e32 v16, v16, v17
	v_add_f32_e32 v6, v6, v16
	v_cvt_pk_bf16_f32 v18, v104, v105
	v_cvt_pk_bf16_f32 v19, v106, v107
	global_store_dwordx2 v[4:5], v[18:19], off offset:1792
	v_lshlrev_b32_e32 v12, 16, v102
	v_and_b32_e32 v13, 0xffff0000, v102
	v_lshlrev_b32_e32 v14, 16, v103
	v_and_b32_e32 v15, 0xffff0000, v103
	v_pk_add_f32 v[110:111], v[110:111], v[14:15]
	v_pk_add_f32 v[108:109], v[108:109], v[12:13]
	v_pk_add_f32 v[110:111], v[118:119], v[110:111]
	v_pk_add_f32 v[108:109], v[116:117], v[108:109]
	v_pk_add_f32 v[110:111], v[126:127], v[110:111]
	v_pk_add_f32 v[108:109], v[124:125], v[108:109]
	v_pk_add_f32 v[110:111], v[134:135], v[110:111]
	v_pk_add_f32 v[108:109], v[132:133], v[108:109]
	v_pk_add_f32 v[110:111], v[142:143], v[110:111]
	v_pk_add_f32 v[108:109], v[140:141], v[108:109]
	v_pk_add_f32 v[110:111], v[150:151], v[110:111]
	v_pk_add_f32 v[108:109], v[148:149], v[108:109]
	v_pk_add_f32 v[110:111], v[158:159], v[110:111]
	v_pk_add_f32 v[108:109], v[156:157], v[108:109]
	v_pk_add_f32 v[110:111], v[166:167], v[110:111]
	v_pk_add_f32 v[108:109], v[164:165], v[108:109]
	v_pk_add_f32 v[110:111], v[174:175], v[110:111]
	v_pk_add_f32 v[108:109], v[172:173], v[108:109]
	v_pk_add_f32 v[110:111], v[182:183], v[110:111]
	v_pk_add_f32 v[108:109], v[180:181], v[108:109]
	v_pk_add_f32 v[110:111], v[190:191], v[110:111]
	v_pk_add_f32 v[108:109], v[188:189], v[108:109]
	v_mul_f32_e32 v16, v109, v109
	v_mul_f32_e32 v17, v111, v111
	v_fmac_f32_e32 v16, v108, v108
	v_fmac_f32_e32 v17, v110, v110
	v_add_f32_e32 v16, v16, v17
	v_add_f32_e32 v6, v6, v16
	v_cvt_pk_bf16_f32 v18, v108, v109
	v_cvt_pk_bf16_f32 v19, v110, v111
	global_store_dwordx2 v[4:5], v[18:19], off offset:2304
	ds_bpermute_b32 v7, v34, v6
	s_waitcnt lgkmcnt(0)
	v_add_f32_e32 v6, v6, v7
	ds_bpermute_b32 v7, v35, v6
	s_waitcnt lgkmcnt(0)
	v_add_f32_e32 v6, v6, v7
	ds_bpermute_b32 v7, v36, v6
	s_waitcnt lgkmcnt(0)
	v_add_f32_e32 v6, v6, v7
	ds_bpermute_b32 v7, v37, v6
	s_waitcnt lgkmcnt(0)
	v_add_f32_e32 v6, v6, v7
	ds_bpermute_b32 v7, v38, v6
	s_waitcnt lgkmcnt(0)
	v_add_f32_e32 v6, v6, v7
	ds_bpermute_b32 v7, v39, v6
	s_and_saveexec_b64 s[16:17], s[12:13]
	s_cbranch_execz .LBB0_1595
	s_add_u32 s10, s82, s2
	s_addc_u32 s11, s83, s3
	s_waitcnt lgkmcnt(0)
	v_add_f32_e32 v4, v6, v7
	global_store_dword v33, v4, s[10:11]
	s_branch .LBB0_1595

.LBB0_2806:
	v_lshl_add_u64 v[4:5], s[82:83], 0, v[2:3]
	v_add_co_u32_e32 v4, vcc, 0xba67000, v4
	v_lshl_add_u64 v[8:9], s[82:83], 0, v[0:1]
	s_nop 0
	v_addc_co_u32_e32 v5, vcc, 0, v5, vcc
	v_add_co_u32_e32 v8, vcc, 0x34a77000, v8
	s_waitcnt lgkmcnt(0)
	s_nop 0
	v_addc_co_u32_e32 v9, vcc, 0, v9, vcc
	global_load_dwordx2 v[100:101], v[4:5], off offset:768
	global_load_dwordx2 v[102:103], v[4:5], off offset:1280
	global_load_dwordx2 v[104:105], v[4:5], off offset:1792
	global_load_dwordx2 v[106:107], v[4:5], off offset:2304
	v_mov_b32_e32 v10, v8
	v_mov_b32_e32 v11, v9
	global_load_dwordx4 v[108:111], v[10:11], off offset:768
	global_load_dwordx4 v[112:115], v[10:11], off offset:1792
	global_load_dwordx4 v[116:119], v[10:11], off offset:2816
	global_load_dwordx4 v[120:123], v[10:11], off offset:3840
	v_add_co_u32_e32 v10, vcc, 0x80000, v10
	s_nop 1
	v_addc_co_u32_e32 v11, vcc, 0, v11, vcc
	global_load_dwordx4 v[124:127], v[10:11], off offset:768
	global_load_dwordx4 v[128:131], v[10:11], off offset:1792
	global_load_dwordx4 v[132:135], v[10:11], off offset:2816
	global_load_dwordx4 v[136:139], v[10:11], off offset:3840
	v_add_co_u32_e32 v10, vcc, 0x80000, v10
	s_nop 1
	v_addc_co_u32_e32 v11, vcc, 0, v11, vcc
	global_load_dwordx4 v[140:143], v[10:11], off offset:768
	global_load_dwordx4 v[144:147], v[10:11], off offset:1792
	global_load_dwordx4 v[148:151], v[10:11], off offset:2816
	global_load_dwordx4 v[152:155], v[10:11], off offset:3840
	v_add_co_u32_e32 v10, vcc, 0x80000, v10
	s_nop 1
	v_addc_co_u32_e32 v11, vcc, 0, v11, vcc
	global_load_dwordx4 v[156:159], v[10:11], off offset:768
	global_load_dwordx4 v[160:163], v[10:11], off offset:1792
	global_load_dwordx4 v[164:167], v[10:11], off offset:2816
	global_load_dwordx4 v[168:171], v[10:11], off offset:3840
	v_add_co_u32_e32 v10, vcc, 0x80000, v10
	s_nop 1
	v_addc_co_u32_e32 v11, vcc, 0, v11, vcc
	global_load_dwordx4 v[172:175], v[10:11], off offset:768
	global_load_dwordx4 v[176:179], v[10:11], off offset:1792
	global_load_dwordx4 v[180:183], v[10:11], off offset:2816
	global_load_dwordx4 v[184:187], v[10:11], off offset:3840
	v_add_co_u32_e32 v10, vcc, 0x80000, v10
	s_nop 1
	v_addc_co_u32_e32 v11, vcc, 0, v11, vcc
	global_load_dwordx4 v[188:191], v[10:11], off offset:768
	global_load_dwordx4 v[192:195], v[10:11], off offset:1792
	global_load_dwordx4 v[196:199], v[10:11], off offset:2816
	global_load_dwordx4 v[200:203], v[10:11], off offset:3840
	v_add_co_u32_e32 v10, vcc, 0x80000, v10
	s_nop 1
	v_addc_co_u32_e32 v11, vcc, 0, v11, vcc
	global_load_dwordx4 v[204:207], v[10:11], off offset:768
	global_load_dwordx4 v[208:211], v[10:11], off offset:1792
	global_load_dwordx4 v[212:215], v[10:11], off offset:2816
	global_load_dwordx4 v[216:219], v[10:11], off offset:3840
	v_add_co_u32_e32 v10, vcc, 0x80000, v10
	s_nop 1
	v_addc_co_u32_e32 v11, vcc, 0, v11, vcc
	global_load_dwordx4 v[220:223], v[10:11], off offset:768
	global_load_dwordx4 v[224:227], v[10:11], off offset:1792
	global_load_dwordx4 v[228:231], v[10:11], off offset:2816
	global_load_dwordx4 v[232:235], v[10:11], off offset:3840
	s_waitcnt vmcnt(0)
	v_lshlrev_b32_e32 v12, 16, v100
	v_and_b32_e32 v13, 0xffff0000, v100
	v_lshlrev_b32_e32 v14, 16, v101
	v_and_b32_e32 v15, 0xffff0000, v101
	v_pk_add_f32 v[110:111], v[110:111], v[14:15]
	v_pk_add_f32 v[108:109], v[108:109], v[12:13]
	v_pk_add_f32 v[110:111], v[126:127], v[110:111]
	v_pk_add_f32 v[108:109], v[124:125], v[108:109]
	v_pk_add_f32 v[110:111], v[142:143], v[110:111]
	v_pk_add_f32 v[108:109], v[140:141], v[108:109]
	v_pk_add_f32 v[110:111], v[158:159], v[110:111]
	v_pk_add_f32 v[108:109], v[156:157], v[108:109]
	v_pk_add_f32 v[110:111], v[174:175], v[110:111]
	v_pk_add_f32 v[108:109], v[172:173], v[108:109]
	v_pk_add_f32 v[110:111], v[190:191], v[110:111]
	v_pk_add_f32 v[108:109], v[188:189], v[108:109]
	v_pk_add_f32 v[110:111], v[206:207], v[110:111]
	v_pk_add_f32 v[108:109], v[204:205], v[108:109]
	v_pk_add_f32 v[110:111], v[222:223], v[110:111]
	v_pk_add_f32 v[108:109], v[220:221], v[108:109]
	v_mul_f32_e32 v16, v109, v109
	v_mul_f32_e32 v17, v111, v111
	v_fmac_f32_e32 v16, v108, v108
	v_fmac_f32_e32 v17, v110, v110
	v_add_f32_e32 v6, v16, v17
	v_cvt_pk_bf16_f32 v18, v108, v109
	v_cvt_pk_bf16_f32 v19, v110, v111
	global_store_dwordx2 v[4:5], v[18:19], off offset:768
	v_lshlrev_b32_e32 v12, 16, v102
	v_and_b32_e32 v13, 0xffff0000, v102
	v_lshlrev_b32_e32 v14, 16, v103
	v_and_b32_e32 v15, 0xffff0000, v103
	v_pk_add_f32 v[114:115], v[114:115], v[14:15]
	v_pk_add_f32 v[112:113], v[112:113], v[12:13]
	v_pk_add_f32 v[114:115], v[130:131], v[114:115]
	v_pk_add_f32 v[112:113], v[128:129], v[112:113]
	v_pk_add_f32 v[114:115], v[146:147], v[114:115]
	v_pk_add_f32 v[112:113], v[144:145], v[112:113]
	v_pk_add_f32 v[114:115], v[162:163], v[114:115]
	v_pk_add_f32 v[112:113], v[160:161], v[112:113]
	v_pk_add_f32 v[114:115], v[178:179], v[114:115]
	v_pk_add_f32 v[112:113], v[176:177], v[112:113]
	v_pk_add_f32 v[114:115], v[194:195], v[114:115]
	v_pk_add_f32 v[112:113], v[192:193], v[112:113]
	v_pk_add_f32 v[114:115], v[210:211], v[114:115]
	v_pk_add_f32 v[112:113], v[208:209], v[112:113]
	v_pk_add_f32 v[114:115], v[226:227], v[114:115]
	v_pk_add_f32 v[112:113], v[224:225], v[112:113]
	v_mul_f32_e32 v16, v113, v113
	v_mul_f32_e32 v17, v115, v115
	v_fmac_f32_e32 v16, v112, v112
	v_fmac_f32_e32 v17, v114, v114
	v_add_f32_e32 v16, v16, v17
	v_add_f32_e32 v6, v6, v16
	v_cvt_pk_bf16_f32 v18, v112, v113
	v_cvt_pk_bf16_f32 v19, v114, v115
	global_store_dwordx2 v[4:5], v[18:19], off offset:1280
	v_lshlrev_b32_e32 v12, 16, v104
	v_and_b32_e32 v13, 0xffff0000, v104
	v_lshlrev_b32_e32 v14, 16, v105
	v_and_b32_e32 v15, 0xffff0000, v105
	v_pk_add_f32 v[118:119], v[118:119], v[14:15]
	v_pk_add_f32 v[116:117], v[116:117], v[12:13]
	v_pk_add_f32 v[118:119], v[134:135], v[118:119]
	v_pk_add_f32 v[116:117], v[132:133], v[116:117]
	v_pk_add_f32 v[118:119], v[150:151], v[118:119]
	v_pk_add_f32 v[116:117], v[148:149], v[116:117]
	v_pk_add_f32 v[118:119], v[166:167], v[118:119]
	v_pk_add_f32 v[116:117], v[164:165], v[116:117]
	v_pk_add_f32 v[118:119], v[182:183], v[118:119]
	v_pk_add_f32 v[116:117], v[180:181], v[116:117]
	v_pk_add_f32 v[118:119], v[198:199], v[118:119]
	v_pk_add_f32 v[116:117], v[196:197], v[116:117]
	v_pk_add_f32 v[118:119], v[214:215], v[118:119]
	v_pk_add_f32 v[116:117], v[212:213], v[116:117]
	v_pk_add_f32 v[118:119], v[230:231], v[118:119]
	v_pk_add_f32 v[116:117], v[228:229], v[116:117]
	v_mul_f32_e32 v16, v117, v117
	v_mul_f32_e32 v17, v119, v119
	v_fmac_f32_e32 v16, v116, v116
	v_fmac_f32_e32 v17, v118, v118
	v_add_f32_e32 v16, v16, v17
	v_add_f32_e32 v6, v6, v16
	v_cvt_pk_bf16_f32 v18, v116, v117
	v_cvt_pk_bf16_f32 v19, v118, v119
	global_store_dwordx2 v[4:5], v[18:19], off offset:1792
	v_lshlrev_b32_e32 v12, 16, v106
	v_and_b32_e32 v13, 0xffff0000, v106
	v_lshlrev_b32_e32 v14, 16, v107
	v_and_b32_e32 v15, 0xffff0000, v107
	v_pk_add_f32 v[122:123], v[122:123], v[14:15]
	v_pk_add_f32 v[120:121], v[120:121], v[12:13]
	v_pk_add_f32 v[122:123], v[138:139], v[122:123]
	v_pk_add_f32 v[120:121], v[136:137], v[120:121]
	v_pk_add_f32 v[122:123], v[154:155], v[122:123]
	v_pk_add_f32 v[120:121], v[152:153], v[120:121]
	v_pk_add_f32 v[122:123], v[170:171], v[122:123]
	v_pk_add_f32 v[120:121], v[168:169], v[120:121]
	v_pk_add_f32 v[122:123], v[186:187], v[122:123]
	v_pk_add_f32 v[120:121], v[184:185], v[120:121]
	v_pk_add_f32 v[122:123], v[202:203], v[122:123]
	v_pk_add_f32 v[120:121], v[200:201], v[120:121]
	v_pk_add_f32 v[122:123], v[218:219], v[122:123]
	v_pk_add_f32 v[120:121], v[216:217], v[120:121]
	v_pk_add_f32 v[122:123], v[234:235], v[122:123]
	v_pk_add_f32 v[120:121], v[232:233], v[120:121]
	v_mul_f32_e32 v16, v121, v121
	v_mul_f32_e32 v17, v123, v123
	v_fmac_f32_e32 v16, v120, v120
	v_fmac_f32_e32 v17, v122, v122
	v_add_f32_e32 v16, v16, v17
	v_add_f32_e32 v6, v6, v16
	v_cvt_pk_bf16_f32 v18, v120, v121
	v_cvt_pk_bf16_f32 v19, v122, v123
	global_store_dwordx2 v[4:5], v[18:19], off offset:2304
	ds_bpermute_b32 v7, v22, v6
	s_waitcnt lgkmcnt(0)
	v_add_f32_e32 v6, v6, v7
	ds_bpermute_b32 v7, v23, v6
	s_waitcnt lgkmcnt(0)
	v_add_f32_e32 v6, v6, v7
	ds_bpermute_b32 v7, v24, v6
	s_waitcnt lgkmcnt(0)
	v_add_f32_e32 v6, v6, v7
	ds_bpermute_b32 v7, v25, v6
	s_waitcnt lgkmcnt(0)
	v_add_f32_e32 v6, v6, v7
	ds_bpermute_b32 v7, v26, v6
	s_waitcnt lgkmcnt(0)
	v_add_f32_e32 v6, v6, v7
	ds_bpermute_b32 v7, v27, v6
	s_and_saveexec_b64 s[16:17], s[8:9]
	s_cbranch_execz .LBB0_2805
	s_add_u32 s10, s82, s2
	s_waitcnt lgkmcnt(0)
	v_add_f32_e32 v4, v6, v7
	s_addc_u32 s11, s83, s3
	global_store_dword v21, v4, s[10:11]
	s_branch .LBB0_2805

.LBB0_3098:
	v_lshl_add_u64 v[4:5], s[82:83], 0, v[2:3]
	v_add_co_u32_e32 v4, vcc, 0xba67000, v4
	v_lshl_add_u64 v[8:9], s[82:83], 0, v[0:1]
	s_nop 0
	v_addc_co_u32_e32 v5, vcc, 0, v5, vcc
	v_add_co_u32_e32 v8, vcc, 0x34a77000, v8
	s_waitcnt lgkmcnt(0)
	s_nop 0
	v_addc_co_u32_e32 v9, vcc, 0, v9, vcc
	global_load_dwordx2 v[100:101], v[4:5], off offset:768
	global_load_dwordx2 v[102:103], v[4:5], off offset:1280
	v_mov_b32_e32 v10, v8
	v_mov_b32_e32 v11, v9
	global_load_dwordx4 v[104:107], v[10:11], off offset:768
	global_load_dwordx4 v[108:111], v[10:11], off offset:1792
	v_add_co_u32_e32 v10, vcc, 0x80000, v10
	s_nop 1
	v_addc_co_u32_e32 v11, vcc, 0, v11, vcc
	global_load_dwordx4 v[112:115], v[10:11], off offset:768
	global_load_dwordx4 v[116:119], v[10:11], off offset:1792
	v_add_co_u32_e32 v10, vcc, 0x80000, v10
	s_nop 1
	v_addc_co_u32_e32 v11, vcc, 0, v11, vcc
	global_load_dwordx4 v[120:123], v[10:11], off offset:768
	global_load_dwordx4 v[124:127], v[10:11], off offset:1792
	v_add_co_u32_e32 v10, vcc, 0x80000, v10
	s_nop 1
	v_addc_co_u32_e32 v11, vcc, 0, v11, vcc
	global_load_dwordx4 v[128:131], v[10:11], off offset:768
	global_load_dwordx4 v[132:135], v[10:11], off offset:1792
	v_add_co_u32_e32 v10, vcc, 0x80000, v10
	s_nop 1
	v_addc_co_u32_e32 v11, vcc, 0, v11, vcc
	global_load_dwordx4 v[136:139], v[10:11], off offset:768
	global_load_dwordx4 v[140:143], v[10:11], off offset:1792
	v_add_co_u32_e32 v10, vcc, 0x80000, v10
	s_nop 1
	v_addc_co_u32_e32 v11, vcc, 0, v11, vcc
	global_load_dwordx4 v[144:147], v[10:11], off offset:768
	global_load_dwordx4 v[148:151], v[10:11], off offset:1792
	v_add_co_u32_e32 v10, vcc, 0x80000, v10
	s_nop 1
	v_addc_co_u32_e32 v11, vcc, 0, v11, vcc
	global_load_dwordx4 v[152:155], v[10:11], off offset:768
	global_load_dwordx4 v[156:159], v[10:11], off offset:1792
	v_add_co_u32_e32 v10, vcc, 0x80000, v10
	s_nop 1
	v_addc_co_u32_e32 v11, vcc, 0, v11, vcc
	global_load_dwordx4 v[160:163], v[10:11], off offset:768
	global_load_dwordx4 v[164:167], v[10:11], off offset:1792
	v_add_co_u32_e32 v10, vcc, 0x80000, v10
	s_nop 1
	v_addc_co_u32_e32 v11, vcc, 0, v11, vcc
	global_load_dwordx4 v[168:171], v[10:11], off offset:768
	global_load_dwordx4 v[172:175], v[10:11], off offset:1792
	v_add_co_u32_e32 v10, vcc, 0x80000, v10
	s_nop 1
	v_addc_co_u32_e32 v11, vcc, 0, v11, vcc
	global_load_dwordx4 v[176:179], v[10:11], off offset:768
	global_load_dwordx4 v[180:183], v[10:11], off offset:1792
	v_add_co_u32_e32 v10, vcc, 0x80000, v10
	s_nop 1
	v_addc_co_u32_e32 v11, vcc, 0, v11, vcc
	global_load_dwordx4 v[184:187], v[10:11], off offset:768
	global_load_dwordx4 v[188:191], v[10:11], off offset:1792
	s_waitcnt vmcnt(0)
	v_lshlrev_b32_e32 v12, 16, v100
	v_and_b32_e32 v13, 0xffff0000, v100
	v_lshlrev_b32_e32 v14, 16, v101
	v_and_b32_e32 v15, 0xffff0000, v101
	v_pk_add_f32 v[106:107], v[106:107], v[14:15]
	v_pk_add_f32 v[104:105], v[104:105], v[12:13]
	v_pk_add_f32 v[106:107], v[114:115], v[106:107]
	v_pk_add_f32 v[104:105], v[112:113], v[104:105]
	v_pk_add_f32 v[106:107], v[122:123], v[106:107]
	v_pk_add_f32 v[104:105], v[120:121], v[104:105]
	v_pk_add_f32 v[106:107], v[130:131], v[106:107]
	v_pk_add_f32 v[104:105], v[128:129], v[104:105]
	v_pk_add_f32 v[106:107], v[138:139], v[106:107]
	v_pk_add_f32 v[104:105], v[136:137], v[104:105]
	v_pk_add_f32 v[106:107], v[146:147], v[106:107]
	v_pk_add_f32 v[104:105], v[144:145], v[104:105]
	v_pk_add_f32 v[106:107], v[154:155], v[106:107]
	v_pk_add_f32 v[104:105], v[152:153], v[104:105]
	v_pk_add_f32 v[106:107], v[162:163], v[106:107]
	v_pk_add_f32 v[104:105], v[160:161], v[104:105]
	v_pk_add_f32 v[106:107], v[170:171], v[106:107]
	v_pk_add_f32 v[104:105], v[168:169], v[104:105]
	v_pk_add_f32 v[106:107], v[178:179], v[106:107]
	v_pk_add_f32 v[104:105], v[176:177], v[104:105]
	v_pk_add_f32 v[106:107], v[186:187], v[106:107]
	v_pk_add_f32 v[104:105], v[184:185], v[104:105]
	v_mul_f32_e32 v16, v105, v105
	v_mul_f32_e32 v17, v107, v107
	v_fmac_f32_e32 v16, v104, v104
	v_fmac_f32_e32 v17, v106, v106
	v_add_f32_e32 v6, v16, v17
	v_cvt_pk_bf16_f32 v18, v104, v105
	v_cvt_pk_bf16_f32 v19, v106, v107
	global_store_dwordx2 v[4:5], v[18:19], off offset:768
	v_lshlrev_b32_e32 v12, 16, v102
	v_and_b32_e32 v13, 0xffff0000, v102
	v_lshlrev_b32_e32 v14, 16, v103
	v_and_b32_e32 v15, 0xffff0000, v103
	v_pk_add_f32 v[110:111], v[110:111], v[14:15]
	v_pk_add_f32 v[108:109], v[108:109], v[12:13]
	v_pk_add_f32 v[110:111], v[118:119], v[110:111]
	v_pk_add_f32 v[108:109], v[116:117], v[108:109]
	v_pk_add_f32 v[110:111], v[126:127], v[110:111]
	v_pk_add_f32 v[108:109], v[124:125], v[108:109]
	v_pk_add_f32 v[110:111], v[134:135], v[110:111]
	v_pk_add_f32 v[108:109], v[132:133], v[108:109]
	v_pk_add_f32 v[110:111], v[142:143], v[110:111]
	v_pk_add_f32 v[108:109], v[140:141], v[108:109]
	v_pk_add_f32 v[110:111], v[150:151], v[110:111]
	v_pk_add_f32 v[108:109], v[148:149], v[108:109]
	v_pk_add_f32 v[110:111], v[158:159], v[110:111]
	v_pk_add_f32 v[108:109], v[156:157], v[108:109]
	v_pk_add_f32 v[110:111], v[166:167], v[110:111]
	v_pk_add_f32 v[108:109], v[164:165], v[108:109]
	v_pk_add_f32 v[110:111], v[174:175], v[110:111]
	v_pk_add_f32 v[108:109], v[172:173], v[108:109]
	v_pk_add_f32 v[110:111], v[182:183], v[110:111]
	v_pk_add_f32 v[108:109], v[180:181], v[108:109]
	v_pk_add_f32 v[110:111], v[190:191], v[110:111]
	v_pk_add_f32 v[108:109], v[188:189], v[108:109]
	v_mul_f32_e32 v16, v109, v109
	v_mul_f32_e32 v17, v111, v111
	v_fmac_f32_e32 v16, v108, v108
	v_fmac_f32_e32 v17, v110, v110
	v_add_f32_e32 v16, v16, v17
	v_add_f32_e32 v6, v6, v16
	v_cvt_pk_bf16_f32 v18, v108, v109
	v_cvt_pk_bf16_f32 v19, v110, v111
	global_store_dwordx2 v[4:5], v[18:19], off offset:1280
	global_load_dwordx2 v[100:101], v[4:5], off offset:1792
	global_load_dwordx2 v[102:103], v[4:5], off offset:2304
	v_mov_b32_e32 v10, v8
	v_mov_b32_e32 v11, v9
	global_load_dwordx4 v[104:107], v[10:11], off offset:2816
	global_load_dwordx4 v[108:111], v[10:11], off offset:3840
	v_add_co_u32_e32 v10, vcc, 0x80000, v10
	s_nop 1
	v_addc_co_u32_e32 v11, vcc, 0, v11, vcc
	global_load_dwordx4 v[112:115], v[10:11], off offset:2816
	global_load_dwordx4 v[116:119], v[10:11], off offset:3840
	v_add_co_u32_e32 v10, vcc, 0x80000, v10
	s_nop 1
	v_addc_co_u32_e32 v11, vcc, 0, v11, vcc
	global_load_dwordx4 v[120:123], v[10:11], off offset:2816
	global_load_dwordx4 v[124:127], v[10:11], off offset:3840
	v_add_co_u32_e32 v10, vcc, 0x80000, v10
	s_nop 1
	v_addc_co_u32_e32 v11, vcc, 0, v11, vcc
	global_load_dwordx4 v[128:131], v[10:11], off offset:2816
	global_load_dwordx4 v[132:135], v[10:11], off offset:3840
	v_add_co_u32_e32 v10, vcc, 0x80000, v10
	s_nop 1
	v_addc_co_u32_e32 v11, vcc, 0, v11, vcc
	global_load_dwordx4 v[136:139], v[10:11], off offset:2816
	global_load_dwordx4 v[140:143], v[10:11], off offset:3840
	v_add_co_u32_e32 v10, vcc, 0x80000, v10
	s_nop 1
	v_addc_co_u32_e32 v11, vcc, 0, v11, vcc
	global_load_dwordx4 v[144:147], v[10:11], off offset:2816
	global_load_dwordx4 v[148:151], v[10:11], off offset:3840
	v_add_co_u32_e32 v10, vcc, 0x80000, v10
	s_nop 1
	v_addc_co_u32_e32 v11, vcc, 0, v11, vcc
	global_load_dwordx4 v[152:155], v[10:11], off offset:2816
	global_load_dwordx4 v[156:159], v[10:11], off offset:3840
	v_add_co_u32_e32 v10, vcc, 0x80000, v10
	s_nop 1
	v_addc_co_u32_e32 v11, vcc, 0, v11, vcc
	global_load_dwordx4 v[160:163], v[10:11], off offset:2816
	global_load_dwordx4 v[164:167], v[10:11], off offset:3840
	v_add_co_u32_e32 v10, vcc, 0x80000, v10
	s_nop 1
	v_addc_co_u32_e32 v11, vcc, 0, v11, vcc
	global_load_dwordx4 v[168:171], v[10:11], off offset:2816
	global_load_dwordx4 v[172:175], v[10:11], off offset:3840
	v_add_co_u32_e32 v10, vcc, 0x80000, v10
	s_nop 1
	v_addc_co_u32_e32 v11, vcc, 0, v11, vcc
	global_load_dwordx4 v[176:179], v[10:11], off offset:2816
	global_load_dwordx4 v[180:183], v[10:11], off offset:3840
	v_add_co_u32_e32 v10, vcc, 0x80000, v10
	s_nop 1
	v_addc_co_u32_e32 v11, vcc, 0, v11, vcc
	global_load_dwordx4 v[184:187], v[10:11], off offset:2816
	global_load_dwordx4 v[188:191], v[10:11], off offset:3840
	s_waitcnt vmcnt(0)
	v_lshlrev_b32_e32 v12, 16, v100
	v_and_b32_e32 v13, 0xffff0000, v100
	v_lshlrev_b32_e32 v14, 16, v101
	v_and_b32_e32 v15, 0xffff0000, v101
	v_pk_add_f32 v[106:107], v[106:107], v[14:15]
	v_pk_add_f32 v[104:105], v[104:105], v[12:13]
	v_pk_add_f32 v[106:107], v[114:115], v[106:107]
	v_pk_add_f32 v[104:105], v[112:113], v[104:105]
	v_pk_add_f32 v[106:107], v[122:123], v[106:107]
	v_pk_add_f32 v[104:105], v[120:121], v[104:105]
	v_pk_add_f32 v[106:107], v[130:131], v[106:107]
	v_pk_add_f32 v[104:105], v[128:129], v[104:105]
	v_pk_add_f32 v[106:107], v[138:139], v[106:107]
	v_pk_add_f32 v[104:105], v[136:137], v[104:105]
	v_pk_add_f32 v[106:107], v[146:147], v[106:107]
	v_pk_add_f32 v[104:105], v[144:145], v[104:105]
	v_pk_add_f32 v[106:107], v[154:155], v[106:107]
	v_pk_add_f32 v[104:105], v[152:153], v[104:105]
	v_pk_add_f32 v[106:107], v[162:163], v[106:107]
	v_pk_add_f32 v[104:105], v[160:161], v[104:105]
	v_pk_add_f32 v[106:107], v[170:171], v[106:107]
	v_pk_add_f32 v[104:105], v[168:169], v[104:105]
	v_pk_add_f32 v[106:107], v[178:179], v[106:107]
	v_pk_add_f32 v[104:105], v[176:177], v[104:105]
	v_pk_add_f32 v[106:107], v[186:187], v[106:107]
	v_pk_add_f32 v[104:105], v[184:185], v[104:105]
	v_mul_f32_e32 v16, v105, v105
	v_mul_f32_e32 v17, v107, v107
	v_fmac_f32_e32 v16, v104, v104
	v_fmac_f32_e32 v17, v106, v106
	v_add_f32_e32 v16, v16, v17
	v_add_f32_e32 v6, v6, v16
	v_cvt_pk_bf16_f32 v18, v104, v105
	v_cvt_pk_bf16_f32 v19, v106, v107
	global_store_dwordx2 v[4:5], v[18:19], off offset:1792
	v_lshlrev_b32_e32 v12, 16, v102
	v_and_b32_e32 v13, 0xffff0000, v102
	v_lshlrev_b32_e32 v14, 16, v103
	v_and_b32_e32 v15, 0xffff0000, v103
	v_pk_add_f32 v[110:111], v[110:111], v[14:15]
	v_pk_add_f32 v[108:109], v[108:109], v[12:13]
	v_pk_add_f32 v[110:111], v[118:119], v[110:111]
	v_pk_add_f32 v[108:109], v[116:117], v[108:109]
	v_pk_add_f32 v[110:111], v[126:127], v[110:111]
	v_pk_add_f32 v[108:109], v[124:125], v[108:109]
	v_pk_add_f32 v[110:111], v[134:135], v[110:111]
	v_pk_add_f32 v[108:109], v[132:133], v[108:109]
	v_pk_add_f32 v[110:111], v[142:143], v[110:111]
	v_pk_add_f32 v[108:109], v[140:141], v[108:109]
	v_pk_add_f32 v[110:111], v[150:151], v[110:111]
	v_pk_add_f32 v[108:109], v[148:149], v[108:109]
	v_pk_add_f32 v[110:111], v[158:159], v[110:111]
	v_pk_add_f32 v[108:109], v[156:157], v[108:109]
	v_pk_add_f32 v[110:111], v[166:167], v[110:111]
	v_pk_add_f32 v[108:109], v[164:165], v[108:109]
	v_pk_add_f32 v[110:111], v[174:175], v[110:111]
	v_pk_add_f32 v[108:109], v[172:173], v[108:109]
	v_pk_add_f32 v[110:111], v[182:183], v[110:111]
	v_pk_add_f32 v[108:109], v[180:181], v[108:109]
	v_pk_add_f32 v[110:111], v[190:191], v[110:111]
	v_pk_add_f32 v[108:109], v[188:189], v[108:109]
	v_mul_f32_e32 v16, v109, v109
	v_mul_f32_e32 v17, v111, v111
	v_fmac_f32_e32 v16, v108, v108
	v_fmac_f32_e32 v17, v110, v110
	v_add_f32_e32 v16, v16, v17
	v_add_f32_e32 v6, v6, v16
	v_cvt_pk_bf16_f32 v18, v108, v109
	v_cvt_pk_bf16_f32 v19, v110, v111
	global_store_dwordx2 v[4:5], v[18:19], off offset:2304
	ds_bpermute_b32 v7, v34, v6
	s_waitcnt lgkmcnt(0)
	v_add_f32_e32 v6, v6, v7
	ds_bpermute_b32 v7, v35, v6
	s_waitcnt lgkmcnt(0)
	v_add_f32_e32 v6, v6, v7
	ds_bpermute_b32 v7, v36, v6
	s_waitcnt lgkmcnt(0)
	v_add_f32_e32 v6, v6, v7
	ds_bpermute_b32 v7, v37, v6
	s_waitcnt lgkmcnt(0)
	v_add_f32_e32 v6, v6, v7
	ds_bpermute_b32 v7, v38, v6
	s_waitcnt lgkmcnt(0)
	v_add_f32_e32 v6, v6, v7
	ds_bpermute_b32 v7, v39, v6
	s_and_saveexec_b64 s[14:15], s[8:9]
	s_cbranch_execz .LBB0_3097
	s_add_u32 s16, s82, s2
	s_addc_u32 s17, s83, s3
	s_waitcnt lgkmcnt(0)
	v_add_f32_e32 v4, v6, v7
	global_store_dword v33, v4, s[16:17]
	s_branch .LBB0_3097

.LBB0_4066:
	v_lshl_add_u64 v[4:5], s[82:83], 0, v[2:3]
	v_add_co_u32_e32 v4, vcc, 0xba67000, v4
	v_lshl_add_u64 v[8:9], s[82:83], 0, v[0:1]
	s_nop 0
	v_addc_co_u32_e32 v5, vcc, 0, v5, vcc
	v_add_co_u32_e32 v8, vcc, 0x34a77000, v8
	s_waitcnt lgkmcnt(0)
	s_nop 0
	v_addc_co_u32_e32 v9, vcc, 0, v9, vcc
	global_load_dwordx2 v[100:101], v[4:5], off offset:768
	global_load_dwordx2 v[102:103], v[4:5], off offset:1280
	global_load_dwordx2 v[104:105], v[4:5], off offset:1792
	global_load_dwordx2 v[106:107], v[4:5], off offset:2304
	v_mov_b32_e32 v10, v8
	v_mov_b32_e32 v11, v9
	global_load_dwordx4 v[108:111], v[10:11], off offset:768
	global_load_dwordx4 v[112:115], v[10:11], off offset:1792
	global_load_dwordx4 v[116:119], v[10:11], off offset:2816
	global_load_dwordx4 v[120:123], v[10:11], off offset:3840
	v_add_co_u32_e32 v10, vcc, 0x80000, v10
	s_nop 1
	v_addc_co_u32_e32 v11, vcc, 0, v11, vcc
	global_load_dwordx4 v[124:127], v[10:11], off offset:768
	global_load_dwordx4 v[128:131], v[10:11], off offset:1792
	global_load_dwordx4 v[132:135], v[10:11], off offset:2816
	global_load_dwordx4 v[136:139], v[10:11], off offset:3840
	v_add_co_u32_e32 v10, vcc, 0x80000, v10
	s_nop 1
	v_addc_co_u32_e32 v11, vcc, 0, v11, vcc
	global_load_dwordx4 v[140:143], v[10:11], off offset:768
	global_load_dwordx4 v[144:147], v[10:11], off offset:1792
	global_load_dwordx4 v[148:151], v[10:11], off offset:2816
	global_load_dwordx4 v[152:155], v[10:11], off offset:3840
	v_add_co_u32_e32 v10, vcc, 0x80000, v10
	s_nop 1
	v_addc_co_u32_e32 v11, vcc, 0, v11, vcc
	global_load_dwordx4 v[156:159], v[10:11], off offset:768
	global_load_dwordx4 v[160:163], v[10:11], off offset:1792
	global_load_dwordx4 v[164:167], v[10:11], off offset:2816
	global_load_dwordx4 v[168:171], v[10:11], off offset:3840
	v_add_co_u32_e32 v10, vcc, 0x80000, v10
	s_nop 1
	v_addc_co_u32_e32 v11, vcc, 0, v11, vcc
	global_load_dwordx4 v[172:175], v[10:11], off offset:768
	global_load_dwordx4 v[176:179], v[10:11], off offset:1792
	global_load_dwordx4 v[180:183], v[10:11], off offset:2816
	global_load_dwordx4 v[184:187], v[10:11], off offset:3840
	v_add_co_u32_e32 v10, vcc, 0x80000, v10
	s_nop 1
	v_addc_co_u32_e32 v11, vcc, 0, v11, vcc
	global_load_dwordx4 v[188:191], v[10:11], off offset:768
	global_load_dwordx4 v[192:195], v[10:11], off offset:1792
	global_load_dwordx4 v[196:199], v[10:11], off offset:2816
	global_load_dwordx4 v[200:203], v[10:11], off offset:3840
	v_add_co_u32_e32 v10, vcc, 0x80000, v10
	s_nop 1
	v_addc_co_u32_e32 v11, vcc, 0, v11, vcc
	global_load_dwordx4 v[204:207], v[10:11], off offset:768
	global_load_dwordx4 v[208:211], v[10:11], off offset:1792
	global_load_dwordx4 v[212:215], v[10:11], off offset:2816
	global_load_dwordx4 v[216:219], v[10:11], off offset:3840
	v_add_co_u32_e32 v10, vcc, 0x80000, v10
	s_nop 1
	v_addc_co_u32_e32 v11, vcc, 0, v11, vcc
	global_load_dwordx4 v[220:223], v[10:11], off offset:768
	global_load_dwordx4 v[224:227], v[10:11], off offset:1792
	global_load_dwordx4 v[228:231], v[10:11], off offset:2816
	global_load_dwordx4 v[232:235], v[10:11], off offset:3840
	s_waitcnt vmcnt(0)
	v_lshlrev_b32_e32 v12, 16, v100
	v_and_b32_e32 v13, 0xffff0000, v100
	v_lshlrev_b32_e32 v14, 16, v101
	v_and_b32_e32 v15, 0xffff0000, v101
	v_pk_add_f32 v[110:111], v[110:111], v[14:15]
	v_pk_add_f32 v[108:109], v[108:109], v[12:13]
	v_pk_add_f32 v[110:111], v[126:127], v[110:111]
	v_pk_add_f32 v[108:109], v[124:125], v[108:109]
	v_pk_add_f32 v[110:111], v[142:143], v[110:111]
	v_pk_add_f32 v[108:109], v[140:141], v[108:109]
	v_pk_add_f32 v[110:111], v[158:159], v[110:111]
	v_pk_add_f32 v[108:109], v[156:157], v[108:109]
	v_pk_add_f32 v[110:111], v[174:175], v[110:111]
	v_pk_add_f32 v[108:109], v[172:173], v[108:109]
	v_pk_add_f32 v[110:111], v[190:191], v[110:111]
	v_pk_add_f32 v[108:109], v[188:189], v[108:109]
	v_pk_add_f32 v[110:111], v[206:207], v[110:111]
	v_pk_add_f32 v[108:109], v[204:205], v[108:109]
	v_pk_add_f32 v[110:111], v[222:223], v[110:111]
	v_pk_add_f32 v[108:109], v[220:221], v[108:109]
	v_mul_f32_e32 v16, v109, v109
	v_mul_f32_e32 v17, v111, v111
	v_fmac_f32_e32 v16, v108, v108
	v_fmac_f32_e32 v17, v110, v110
	v_add_f32_e32 v6, v16, v17
	v_cvt_pk_bf16_f32 v18, v108, v109
	v_cvt_pk_bf16_f32 v19, v110, v111
	global_store_dwordx2 v[4:5], v[18:19], off offset:768
	v_lshlrev_b32_e32 v12, 16, v102
	v_and_b32_e32 v13, 0xffff0000, v102
	v_lshlrev_b32_e32 v14, 16, v103
	v_and_b32_e32 v15, 0xffff0000, v103
	v_pk_add_f32 v[114:115], v[114:115], v[14:15]
	v_pk_add_f32 v[112:113], v[112:113], v[12:13]
	v_pk_add_f32 v[114:115], v[130:131], v[114:115]
	v_pk_add_f32 v[112:113], v[128:129], v[112:113]
	v_pk_add_f32 v[114:115], v[146:147], v[114:115]
	v_pk_add_f32 v[112:113], v[144:145], v[112:113]
	v_pk_add_f32 v[114:115], v[162:163], v[114:115]
	v_pk_add_f32 v[112:113], v[160:161], v[112:113]
	v_pk_add_f32 v[114:115], v[178:179], v[114:115]
	v_pk_add_f32 v[112:113], v[176:177], v[112:113]
	v_pk_add_f32 v[114:115], v[194:195], v[114:115]
	v_pk_add_f32 v[112:113], v[192:193], v[112:113]
	v_pk_add_f32 v[114:115], v[210:211], v[114:115]
	v_pk_add_f32 v[112:113], v[208:209], v[112:113]
	v_pk_add_f32 v[114:115], v[226:227], v[114:115]
	v_pk_add_f32 v[112:113], v[224:225], v[112:113]
	v_mul_f32_e32 v16, v113, v113
	v_mul_f32_e32 v17, v115, v115
	v_fmac_f32_e32 v16, v112, v112
	v_fmac_f32_e32 v17, v114, v114
	v_add_f32_e32 v16, v16, v17
	v_add_f32_e32 v6, v6, v16
	v_cvt_pk_bf16_f32 v18, v112, v113
	v_cvt_pk_bf16_f32 v19, v114, v115
	global_store_dwordx2 v[4:5], v[18:19], off offset:1280
	v_lshlrev_b32_e32 v12, 16, v104
	v_and_b32_e32 v13, 0xffff0000, v104
	v_lshlrev_b32_e32 v14, 16, v105
	v_and_b32_e32 v15, 0xffff0000, v105
	v_pk_add_f32 v[118:119], v[118:119], v[14:15]
	v_pk_add_f32 v[116:117], v[116:117], v[12:13]
	v_pk_add_f32 v[118:119], v[134:135], v[118:119]
	v_pk_add_f32 v[116:117], v[132:133], v[116:117]
	v_pk_add_f32 v[118:119], v[150:151], v[118:119]
	v_pk_add_f32 v[116:117], v[148:149], v[116:117]
	v_pk_add_f32 v[118:119], v[166:167], v[118:119]
	v_pk_add_f32 v[116:117], v[164:165], v[116:117]
	v_pk_add_f32 v[118:119], v[182:183], v[118:119]
	v_pk_add_f32 v[116:117], v[180:181], v[116:117]
	v_pk_add_f32 v[118:119], v[198:199], v[118:119]
	v_pk_add_f32 v[116:117], v[196:197], v[116:117]
	v_pk_add_f32 v[118:119], v[214:215], v[118:119]
	v_pk_add_f32 v[116:117], v[212:213], v[116:117]
	v_pk_add_f32 v[118:119], v[230:231], v[118:119]
	v_pk_add_f32 v[116:117], v[228:229], v[116:117]
	v_mul_f32_e32 v16, v117, v117
	v_mul_f32_e32 v17, v119, v119
	v_fmac_f32_e32 v16, v116, v116
	v_fmac_f32_e32 v17, v118, v118
	v_add_f32_e32 v16, v16, v17
	v_add_f32_e32 v6, v6, v16
	v_cvt_pk_bf16_f32 v18, v116, v117
	v_cvt_pk_bf16_f32 v19, v118, v119
	global_store_dwordx2 v[4:5], v[18:19], off offset:1792
	v_lshlrev_b32_e32 v12, 16, v106
	v_and_b32_e32 v13, 0xffff0000, v106
	v_lshlrev_b32_e32 v14, 16, v107
	v_and_b32_e32 v15, 0xffff0000, v107
	v_pk_add_f32 v[122:123], v[122:123], v[14:15]
	v_pk_add_f32 v[120:121], v[120:121], v[12:13]
	v_pk_add_f32 v[122:123], v[138:139], v[122:123]
	v_pk_add_f32 v[120:121], v[136:137], v[120:121]
	v_pk_add_f32 v[122:123], v[154:155], v[122:123]
	v_pk_add_f32 v[120:121], v[152:153], v[120:121]
	v_pk_add_f32 v[122:123], v[170:171], v[122:123]
	v_pk_add_f32 v[120:121], v[168:169], v[120:121]
	v_pk_add_f32 v[122:123], v[186:187], v[122:123]
	v_pk_add_f32 v[120:121], v[184:185], v[120:121]
	v_pk_add_f32 v[122:123], v[202:203], v[122:123]
	v_pk_add_f32 v[120:121], v[200:201], v[120:121]
	v_pk_add_f32 v[122:123], v[218:219], v[122:123]
	v_pk_add_f32 v[120:121], v[216:217], v[120:121]
	v_pk_add_f32 v[122:123], v[234:235], v[122:123]
	v_pk_add_f32 v[120:121], v[232:233], v[120:121]
	v_mul_f32_e32 v16, v121, v121
	v_mul_f32_e32 v17, v123, v123
	v_fmac_f32_e32 v16, v120, v120
	v_fmac_f32_e32 v17, v122, v122
	v_add_f32_e32 v16, v16, v17
	v_add_f32_e32 v6, v6, v16
	v_cvt_pk_bf16_f32 v18, v120, v121
	v_cvt_pk_bf16_f32 v19, v122, v123
	global_store_dwordx2 v[4:5], v[18:19], off offset:2304
	ds_bpermute_b32 v7, v24, v6
	s_waitcnt lgkmcnt(0)
	v_add_f32_e32 v6, v6, v7
	ds_bpermute_b32 v7, v25, v6
	s_waitcnt lgkmcnt(0)
	v_add_f32_e32 v6, v6, v7
	ds_bpermute_b32 v7, v26, v6
	s_waitcnt lgkmcnt(0)
	v_add_f32_e32 v6, v6, v7
	ds_bpermute_b32 v7, v27, v6
	s_waitcnt lgkmcnt(0)
	v_add_f32_e32 v6, v6, v7
	ds_bpermute_b32 v7, v28, v6
	s_waitcnt lgkmcnt(0)
	v_add_f32_e32 v6, v6, v7
	ds_bpermute_b32 v7, v29, v6
	s_and_saveexec_b64 s[14:15], s[8:9]
	s_cbranch_execz .LBB0_4065
	s_add_u32 s16, s82, s2
	s_addc_u32 s17, s83, s3
	s_waitcnt lgkmcnt(0)
	v_add_f32_e32 v4, v6, v7
	global_store_dword v23, v4, s[16:17]
	s_branch .LBB0_4065
